# LDS-DMA K/V tile staging extended to differential-attention loops (modes 2,3)
# speedup vs baseline: 1.0812x; 1.0059x over previous
; __device__ __forceinline__ int v_st(int k, int c) { const int kk = (k & ~0xC) | ((k & 4) << 1) | ((k & 8) >> 1); return ((kk >> 3) * 4 + (c >> 5)) * 512 + ((kk & 7) * 32 + (c & 31)) * 2; }
; __device__ __forceinline__ int v_rd_base(int lane) { return ((lane & 3) << 3) | (((lane >> 2) & 3) << 6) | (((lane >> 4) & 1) << 5) | (((lane >> 5) & 1) << 8); }
; #define SLOAD(i, k0) do { sr_[i].vs0 = *reinterpret_cast<const bf16x8*>(&Vh[(size_t)((k0) + sr) * LDQK + sc]); sr_[i].vs1 = *reinterpret_cast<const bf16x8*>(&Vh[(size_t)((k0) + 32 + sr) * LDQK + sc]); \
;     sr_[i].ks0 = *reinterpret_cast<const bf16x8*>(&Kh[(size_t)((k0) + sr) * LDQK + sc]); sr_[i].ks1 = *reinterpret_cast<const bf16x8*>(&Kh[(size_t)((k0) + 32 + sr) * LDQK + sc]); } while (0)
; #define SWRITE(off, i) do { *(bf16x8*)(V_lds + (off) + vst0) = sr_[i].vs0;          \
;     *(bf16x8*)(V_lds + (off) + vst1) = sr_[i].vs1; int kc = sc * 2;               \
;     *(bf16x8*)(K_lds + (off) + KSWZ(sr, kc)) = sr_[i].ks0;                       \
;     *(bf16x8*)(K_lds + (off) + KSWZ(32 + sr, kc)) = sr_[i].ks1; } while (0)
; #define SWAIT() asm volatile("s_waitcnt vmcnt(4)" ::: "memory")
; #define PSM(P0, P1, MN, AL, J) partialSM<MODE>(P0, P1, m_reg, MN, AL, relq + 64 * (J), relwmin + 64 * (J), relwmax + 64 * (J), lut)
; template <int MODE>
; __device__ __forceinline__ void attn_body(const bf16_t* __restrict__ Qb, const bf16_t* __restrict__ Kh, const bf16_t* __restrict__ Vh, int NT, int krel0,
;                                           char* lds, const float* __restrict__ lutg, const AttnEpi& E) {
;     ...
;   const int sr = tid >> 4, sc = (tid & 15) * 8, vst0 = v_st(sr, sc), vst1 = v_st(32 + sr, sc);
;   const int vb0 = (int)(uintptr_t)V_lds + v_rd_base(lane);
;   struct { bf16x8 vs0, vs1, ks0, ks1; } sr_[2];
;     ...
;   const int relq = krel0 - (wid * 32 + r32) + 4 * hi, relwmin = krel0 - (wid * 32 + 31), relwmax = krel0 + 63 - wid * 32;
;     ...
;   f32x16 pA0, pA1, pB0, pB1; float mnA, mnB, alA, alB; bf16x8 pa0, pa1, pa2, pa3;
;   constexpr int SE = 0, SO = 1;
;   SLOAD(SE, 0); SLOAD(SO, 64); asm volatile("s_waitcnt vmcnt(4)" ::: "memory"); SWRITE(0, SE); __syncthreads();
;   qkt<ND0, DOFF>(pA0, pA1, K_lds, qr, r32, hi); PSM(pA0, pA1, mnA, alA, 0);
;   if (2 < NT) SLOAD(SE, 2 * 64);
;   SWAIT(); SWRITE(SHM_V, SO);
;   int op = 0, oq = SHM_V, ow = 2 * SHM_V;
.LBB0_131:
	s_or_b64 exec, exec, s[64:65]
	v_add_u32_e32 v0, 0xa0, v50
	s_movk_i32 s64, 0x1200
	s_nop 3
	v_mad_i64_i32 v[2:3], s[6:7], v0, s64, 0
	v_add_u32_e32 v0, 0x80, v50
	v_or_b32_e32 v2, v2, v51
	v_mad_i64_i32 v[6:7], s[6:7], v0, s64, 0
	v_lshlrev_b64 v[2:3], 1, v[2:3]
	v_or_b32_e32 v6, v6, v51
	v_lshl_add_u64 v[4:5], s[58:59], 0, v[2:3]
	v_lshlrev_b64 v[6:7], 1, v[6:7]
	v_lshl_add_u64 v[2:3], s[0:1], 0, v[2:3]
	v_lshl_add_u64 v[8:9], s[58:59], 0, v[6:7]
	global_load_dwordx4 v[150:153], v[4:5], off
	global_load_dwordx4 v[146:149], v[8:9], off
	v_lshl_add_u64 v[4:5], s[0:1], 0, v[6:7]
	global_load_dwordx4 v[158:161], v[2:3], off
	global_load_dwordx4 v[154:157], v[4:5], off
	v_and_b32_e32 v0, 63, v188
	v_lshlrev_b32_e32 v3, 4, v0
	v_lshlrev_b32_e32 v2, 3, v0
	v_and_b32_e32 v3, 0xc0, v3
	v_lshlrev_b32_e32 v4, 1, v0
	v_and_or_b32 v3, v2, 24, v3
	v_and_b32_e32 v4, 32, v4
	v_and_b32_e32 v2, 0x100, v2
	s_cmp_lg_u32 0, -1
	v_or3_b32 v2, v3, v4, v2
	s_cselect_b32 s6, 0, 0
	v_add_u32_e32 v218, s6, v2
	v_and_b32_e32 v2, 0x3fffffc0, v188
	v_add_u32_e32 v3, s75, v211
	v_ashrrev_i32_e32 v51, 31, v50
	v_lshl_add_u32 v2, v2, 2, s89
	s_waitcnt vmcnt(4)
	s_waitcnt vmcnt(7)
	ds_write_b128 v56, v[34:37] offset:16384
	s_waitcnt vmcnt(5)
	ds_write_b128 v57, v[38:41] offset:16384
	ds_write_b128 v3, v[42:45]
	v_add_u32_e32 v3, s75, v212
	s_waitcnt vmcnt(4)
	ds_write_b128 v3, v[46:49]
	v_cmp_gt_u32_e64 s[6:7], 32, v0
	v_lshl_add_u32 v209, v52, 2, v2
	v_lshl_add_u32 v208, v54, 2, v2
	v_sub_u32_e32 v0, v54, v52
	v_lshl_add_u64 v[2:3], v[50:51], 0, s[2:3]
	s_movk_i32 s66, 0x2400
	v_sub_u32_e32 v222, v0, v53
	v_mad_u64_u32 v[4:5], s[64:65], v2, s66, 0
	v_and_b32_e32 v0, 15, v188
	v_mad_i32_i24 v3, v3, s66, v5
	v_or_b32_e32 v2, s82, v4
	v_lshlrev_b32_e32 v0, 4, v0
	v_readlane_b32 s64, v254, 14
	v_lshl_add_u64 v[2:3], v[2:3], 0, v[0:1]
	v_readlane_b32 s65, v254, 15
	v_mov_b32_e32 v14, v1
	v_mov_b32_e32 v15, v1
	v_sub_u32_e32 v220, 0, v55
	v_sub_u32_e32 v221, 0, v53
	v_lshl_add_u64 v[190:191], s[64:65], 0, v[2:3]
	v_mov_b32_e32 v0, v1
	v_mov_b32_e32 v2, v1
	v_mov_b32_e32 v3, v1
	v_mov_b32_e32 v4, v1
	v_mov_b32_e32 v5, v1
	v_mov_b32_e32 v6, v1
	v_mov_b32_e32 v7, v1
	v_mov_b32_e32 v8, v1
	v_mov_b32_e32 v9, v1
	v_mov_b32_e32 v10, v1
	v_mov_b32_e32 v11, v1
	v_mov_b32_e32 v12, v1
	v_mov_b32_e32 v13, v1
	v_mov_b64_e32 v[64:65], v[14:15]
	v_mov_b64_e32 v[48:49], v[14:15]
	v_mov_b64_e32 v[32:33], v[14:15]
	v_mov_b64_e32 v[62:63], v[12:13]
	v_mov_b64_e32 v[60:61], v[10:11]
	v_mov_b64_e32 v[58:59], v[8:9]
	v_mov_b64_e32 v[56:57], v[6:7]
	v_mov_b64_e32 v[54:55], v[4:5]
	v_mov_b64_e32 v[52:53], v[2:3]
	v_mov_b64_e32 v[50:51], v[0:1]
	v_mov_b64_e32 v[46:47], v[12:13]
	v_mov_b64_e32 v[44:45], v[10:11]
	v_mov_b64_e32 v[42:43], v[8:9]
	v_mov_b64_e32 v[40:41], v[6:7]
	v_mov_b64_e32 v[38:39], v[4:5]
	v_mov_b64_e32 v[36:37], v[2:3]
	v_mov_b64_e32 v[34:35], v[0:1]
	v_mov_b64_e32 v[30:31], v[12:13]
	v_mov_b64_e32 v[28:29], v[10:11]
	v_mov_b64_e32 v[26:27], v[8:9]
	v_mov_b64_e32 v[24:25], v[6:7]
	v_mov_b64_e32 v[22:23], v[4:5]
	v_mov_b64_e32 v[20:21], v[2:3]
	v_mov_b64_e32 v[18:19], v[0:1]
	v_mov_b64_e32 v[16:17], v[14:15]
	s_mov_b32 s80, 0
	s_mov_b32 s81, 2
	s_movk_i32 s83, 0x2400
	s_mov_b32 s74, s82
	v_mov_b32_e32 v210, 0
	s_movk_i32 s82, 0x4000
	s_mov_b32 s64, 0x8000
	v_mov_b64_e32 v[14:15], v[12:13]
	v_mov_b64_e32 v[12:13], v[10:11]
	v_mov_b64_e32 v[10:11], v[8:9]
	v_mov_b64_e32 v[8:9], v[6:7]
	v_mov_b64_e32 v[6:7], v[4:5]
	v_mov_b64_e32 v[4:5], v[2:3]
	v_mov_b64_e32 v[2:3], v[0:1]
	s_waitcnt vmcnt(0)
	v_readfirstlane_b32 s31, v179
	s_nop 3
	s_lshr_b32 s31, s31, 6
	s_lshl_b32 s30, s31, 11
	v_and_b32_e32 v150, 63, v179
	v_bfe_u32 v151, v150, 2, 3
	s_lshl_b32 s29, s31, 3
	v_or_b32_e32 v151, s29, v151
	v_and_b32_e32 v152, 4, v151
	v_lshlrev_b32_e32 v152, 1, v152
	v_and_b32_e32 v153, 8, v151
	v_lshrrev_b32_e32 v153, 1, v153
	v_and_b32_e32 v151, 0xfffffff3, v151
	v_or3_b32 v151, v151, v152, v153
	v_mul_u32_u24_e32 v151, 0x2400, v151
	v_lshrrev_b32_e32 v152, 5, v150
	v_lshlrev_b32_e32 v152, 6, v152
	v_and_b32_e32 v153, 3, v150
	v_lshlrev_b32_e32 v153, 4, v153
	v_add3_u32 v248, v151, v152, v153
	v_add_u32_e32 v249, 0x80, v248
	v_lshrrev_b32_e32 v151, 4, v150
	v_add_u32_e32 v151, s29, v151
	v_and_b32_e32 v152, 15, v150
	v_and_b32_e32 v153, 15, v151
	v_xor_b32_e32 v153, v152, v153
	v_mul_u32_u24_e32 v154, 0x2400, v151
	v_lshl_add_u32 v250, v153, 4, v154
	v_add_u32_e32 v151, 4, v151
	v_and_b32_e32 v153, 15, v151
	v_xor_b32_e32 v153, v152, v153
	v_mul_u32_u24_e32 v154, 0x2400, v151
	v_lshl_add_u32 v251, v153, 4, v154
	v_readfirstlane_b32 s26, v190
	v_readfirstlane_b32 s27, v191
	s_mul_i32 s29, s31, 0x9000
	s_add_u32 s29, s29, 0x168000
	s_sub_u32 s26, s26, s29
	s_subb_u32 s27, s27, 0
	s_sub_u32 s28, s26, 0x200
	s_subb_u32 s29, s27, 0
; #define SBAR() __builtin_amdgcn_sched_barrier(0)
; #define SLOAD(i, k0) do { sr_[i].vs0 = *reinterpret_cast<const bf16x8*>(&Vh[(size_t)((k0) + sr) * LDQK + sc]); sr_[i].vs1 = *reinterpret_cast<const bf16x8*>(&Vh[(size_t)((k0) + 32 + sr) * LDQK + sc]); \
;     sr_[i].ks0 = *reinterpret_cast<const bf16x8*>(&Kh[(size_t)((k0) + sr) * LDQK + sc]); sr_[i].ks1 = *reinterpret_cast<const bf16x8*>(&Kh[(size_t)((k0) + 32 + sr) * LDQK + sc]); } while (0)
; #define PSM(P0, P1, MN, AL, J) partialSM<MODE>(P0, P1, m_reg, MN, AL, relq + 64 * (J), relwmin + 64 * (J), relwmax + 64 * (J), lut)
; template <int MODE>
; __device__ __forceinline__ void partialSM(f32x16& p0, f32x16& p1, float& m_reg, float& mn, float& alpha, int relh, int relw_min, int relw_max, const float* lut) {
;     ...
;       if (relw_max <= -128) { nearT = false; cfar = lut[0]; }
;       else if (relw_min >= 128) { nearT = false; cfar = lut[258]; }
; template <int MODE>
; __device__ __forceinline__ void attn_body(const bf16_t* __restrict__ Qb, const bf16_t* __restrict__ Kh, const bf16_t* __restrict__ Vh, int NT, int krel0,
;                                           char* lds, const float* __restrict__ lutg, const AttnEpi& E) {
;     ...
;   for (int j = 1; j + 1 < NT; j += 2) {
;     __syncthreads();
;     SBAR(); qkt<ND0, DOFF>(pB0, pB1, K_lds + oq, qr, r32, hi);
;     finishSM(pA0, pA1, alA, l_reg, pa0, pa1, pa2, pa3); SBAR();
;     SLOAD(SO, (j + 2) * 64); SBAR();
;     pv_d0(o, vb0 + op, pa0, pa1, pa2, pa3); PSM(pB0, pB1, mnB, alB, j);
.LBB0_132:
	v_readfirstlane_b32 s20, v221
	v_readfirstlane_b32 s21, v220
	s_nop 3
	s_add_i32 s22, s20, s77
	s_addk_i32 s22, 0x7f
	s_add_i32 s23, s21, s77
	s_addk_i32 s23, 0x40
	s_add_i32 s24, s22, 64
	s_add_i32 s25, s23, 64
	s_mov_b32 s79, s64
	s_waitcnt vmcnt(0) lgkmcnt(0)
	s_barrier
	s_add_i32 m0, s79, s30
	s_nop 0
	global_load_lds_dwordx4 v248, s[26:27]
	s_add_i32 m0, m0, 0x400
	s_nop 0
	global_load_lds_dwordx4 v249, s[26:27]
	s_add_i32 m0, m0, 0xbc00
	s_nop 0
	global_load_lds_dwordx4 v250, s[28:29]
	s_add_i32 m0, m0, 0x400
	s_nop 0
	global_load_lds_dwordx4 v251, s[28:29]
	s_add_u32 s26, s26, 0x90000
	s_addc_u32 s27, s27, 0
	s_add_u32 s28, s28, 0x90000
	s_addc_u32 s29, s29, 0
	s_add_i32 s64, s82, 0
	v_add_u32_e32 v0, s64, v213
	ds_read_b128 v[98:101], v0 offset:49152
	ds_read_b128 v[102:105], v0 offset:57344
	v_add_u32_e32 v0, s64, v214
	ds_read_b128 v[162:165], v0 offset:49152
	ds_read_b128 v[166:169], v0 offset:57344
	v_add_u32_e32 v0, s64, v215
	s_waitcnt lgkmcnt(3)
	v_mfma_f32_32x32x16_bf16 v[114:129], v[98:101], v[142:145], 0
	s_waitcnt lgkmcnt(2)
	v_mfma_f32_32x32x16_bf16 v[98:113], v[102:105], v[142:145], 0
	s_waitcnt lgkmcnt(1)
	v_mfma_f32_32x32x16_bf16 v[114:129], v[162:165], v[138:141], v[114:129]
	s_waitcnt lgkmcnt(0)
	v_mfma_f32_32x32x16_bf16 v[98:113], v[166:169], v[138:141], v[98:113]
	ds_read_b128 v[162:165], v0 offset:49152
	ds_read_b128 v[166:169], v0 offset:57344
	v_add_u32_e32 v0, s64, v216
	s_waitcnt lgkmcnt(1)
	v_mfma_f32_32x32x16_bf16 v[114:129], v[162:165], v[134:137], v[114:129]
	s_waitcnt lgkmcnt(0)
	v_mfma_f32_32x32x16_bf16 v[98:113], v[166:169], v[134:137], v[98:113]
	ds_read_b128 v[162:165], v0 offset:49152
	ds_read_b128 v[166:169], v0 offset:57344
	v_exp_f32_e32 v0, v82
	v_exp_f32_e32 v82, v83
	v_exp_f32_e32 v83, v84
	v_exp_f32_e32 v84, v85
	v_exp_f32_e32 v85, v86
	v_exp_f32_e32 v86, v87
	v_exp_f32_e32 v87, v88
	v_exp_f32_e32 v88, v89
	v_exp_f32_e32 v89, v90
	v_exp_f32_e32 v90, v91
	v_exp_f32_e32 v91, v92
	v_exp_f32_e32 v92, v93
	v_exp_f32_e32 v93, v94
	v_exp_f32_e32 v94, v95
	v_exp_f32_e32 v95, v96
	v_exp_f32_e32 v96, v97
	v_add_f32_e32 v97, v67, v66
	v_add_f32_e32 v97, v68, v97
	v_add_f32_e32 v97, v69, v97
	v_add_f32_e32 v97, v70, v97
	v_add_f32_e32 v97, v71, v97
	v_add_f32_e32 v97, v72, v97
	v_add_f32_e32 v97, v73, v97
	v_add_f32_e32 v97, v74, v97
	v_add_f32_e32 v97, v75, v97
	v_add_f32_e32 v97, v76, v97
	v_add_f32_e32 v97, v77, v97
	v_add_f32_e32 v97, v78, v97
	v_add_f32_e32 v97, v79, v97
	v_add_f32_e32 v97, v80, v97
	v_add_f32_e32 v97, v81, v97
	v_add_f32_e32 v97, v0, v97
	v_add_f32_e32 v97, v82, v97
	v_add_f32_e32 v97, v83, v97
	v_add_f32_e32 v97, v84, v97
	v_add_f32_e32 v97, v85, v97
	v_add_f32_e32 v97, v86, v97
	v_add_f32_e32 v97, v87, v97
	v_add_f32_e32 v97, v88, v97
	v_add_f32_e32 v97, v89, v97
	v_add_f32_e32 v97, v90, v97
	s_waitcnt lgkmcnt(1)
	v_mfma_f32_32x32x16_bf16 v[114:129], v[162:165], v[130:133], v[114:129]
	v_add_f32_e32 v97, v91, v97
	v_add_f32_e32 v97, v92, v97
	v_add_f32_e32 v97, v93, v97
	v_add_f32_e32 v97, v94, v97
	v_add_f32_e32 v97, v95, v97
	v_add_f32_e32 v223, v96, v97
	v_mov_b32_e32 v224, v223
	s_waitcnt lgkmcnt(0)
	v_mfma_f32_32x32x16_bf16 v[98:113], v[166:169], v[130:133], v[98:113]
	v_cvt_pk_bf16_f32 v66, v66, v67
	v_cvt_pk_bf16_f32 v67, v68, v69
	v_cvt_pk_bf16_f32 v68, v70, v71
	v_cvt_pk_bf16_f32 v69, v72, v73
	v_cvt_pk_bf16_f32 v70, v74, v75
	v_cvt_pk_bf16_f32 v71, v76, v77
	v_cvt_pk_bf16_f32 v72, v78, v79
	v_cvt_pk_bf16_f32 v73, v80, v81
	v_cvt_pk_bf16_f32 v74, v0, v82
	v_cvt_pk_bf16_f32 v75, v83, v84
	v_cvt_pk_bf16_f32 v76, v85, v86
	v_cvt_pk_bf16_f32 v77, v87, v88
	v_cvt_pk_bf16_f32 v78, v89, v90
	v_cvt_pk_bf16_f32 v79, v91, v92
	v_cvt_pk_bf16_f32 v80, v93, v94
	v_cvt_pk_bf16_f32 v81, v95, v96
	v_permlane32_swap_b32_e32 v223, v224
	v_permlane32_swap_b32_e32 v66, v68
	v_permlane32_swap_b32_e32 v67, v69
	v_permlane32_swap_b32_e32 v70, v72
	v_permlane32_swap_b32_e32 v71, v73
	v_permlane32_swap_b32_e32 v74, v76
	v_permlane32_swap_b32_e32 v75, v77
	v_permlane32_swap_b32_e32 v78, v80
	v_permlane32_swap_b32_e32 v79, v81
	v_add_u32_e32 v0, s80, v218
	ds_read_b64_tr_b16 v[82:83], v0 offset:0
	ds_read_b64_tr_b16 v[84:85], v0 offset:0x800
	ds_read_b64_tr_b16 v[86:87], v0 offset:0x1000
	ds_read_b64_tr_b16 v[88:89], v0 offset:0x1800
	ds_read_b64_tr_b16 v[90:91], v0 offset:0x2000
	ds_read_b64_tr_b16 v[92:93], v0 offset:0x2800
	ds_read_b64_tr_b16 v[94:95], v0 offset:0x3000
	ds_read_b64_tr_b16 v[96:97], v0 offset:0x3800
	s_waitcnt lgkmcnt(0)
	s_nop 0
	v_mfma_f32_32x32x16_bf16 v[50:65], v[66:69], v[82:85], v[50:65]
	ds_read_b64_tr_b16 v[82:83], v0 offset:0x200
	ds_read_b64_tr_b16 v[84:85], v0 offset:0xa00
	v_mfma_f32_32x32x16_bf16 v[50:65], v[70:73], v[86:89], v[50:65]
	ds_read_b64_tr_b16 v[86:87], v0 offset:0x1200
	ds_read_b64_tr_b16 v[88:89], v0 offset:0x1a00
	v_mfma_f32_32x32x16_bf16 v[50:65], v[74:77], v[90:93], v[50:65]
	ds_read_b64_tr_b16 v[90:91], v0 offset:0x2200
	ds_read_b64_tr_b16 v[92:93], v0 offset:0x2a00
	v_mfma_f32_32x32x16_bf16 v[50:65], v[78:81], v[94:97], v[50:65]
	ds_read_b64_tr_b16 v[94:95], v0 offset:0x3200
	ds_read_b64_tr_b16 v[96:97], v0 offset:0x3a00
	s_waitcnt lgkmcnt(0)
	v_mfma_f32_32x32x16_bf16 v[34:49], v[66:69], v[82:85], v[34:49]
	ds_read_b64_tr_b16 v[82:83], v0 offset:0x400
	ds_read_b64_tr_b16 v[84:85], v0 offset:0xc00
	v_mfma_f32_32x32x16_bf16 v[34:49], v[70:73], v[86:89], v[34:49]
	ds_read_b64_tr_b16 v[86:87], v0 offset:0x1400
	ds_read_b64_tr_b16 v[88:89], v0 offset:0x1c00
	v_mfma_f32_32x32x16_bf16 v[34:49], v[74:77], v[90:93], v[34:49]
	ds_read_b64_tr_b16 v[90:91], v0 offset:0x2400
	ds_read_b64_tr_b16 v[92:93], v0 offset:0x2c00
	v_mfma_f32_32x32x16_bf16 v[34:49], v[78:81], v[94:97], v[34:49]
	ds_read_b64_tr_b16 v[94:95], v0 offset:0x3400
	ds_read_b64_tr_b16 v[96:97], v0 offset:0x3c00
	s_waitcnt lgkmcnt(0)
	v_mfma_f32_32x32x16_bf16 v[18:33], v[66:69], v[82:85], v[18:33]
	ds_read_b64_tr_b16 v[82:83], v0 offset:0x600
	ds_read_b64_tr_b16 v[84:85], v0 offset:0xe00
	v_mfma_f32_32x32x16_bf16 v[18:33], v[70:73], v[86:89], v[18:33]
	ds_read_b64_tr_b16 v[86:87], v0 offset:0x1600
	ds_read_b64_tr_b16 v[88:89], v0 offset:0x1e00
	v_mfma_f32_32x32x16_bf16 v[18:33], v[74:77], v[90:93], v[18:33]
	ds_read_b64_tr_b16 v[90:91], v0 offset:0x2600
	ds_read_b64_tr_b16 v[92:93], v0 offset:0x2e00
	v_mfma_f32_32x32x16_bf16 v[18:33], v[78:81], v[94:97], v[18:33]
	ds_read_b64_tr_b16 v[94:95], v0 offset:0x3600
	ds_read_b64_tr_b16 v[96:97], v0 offset:0x3e00
	s_waitcnt lgkmcnt(0)
	v_mfma_f32_32x32x16_bf16 v[2:17], v[66:69], v[82:85], v[2:17]
	s_cmp_gt_i32 s95, s22
	s_cselect_b64 s[64:65], -1, 0
	s_cmp_lt_i32 s15, s22
	s_cselect_b64 vcc, -1, 0
	v_mov_b32_e32 v229, s76
	v_mfma_f32_32x32x16_bf16 v[2:17], v[70:73], v[86:89], v[2:17]
	v_mfma_f32_32x32x16_bf16 v[2:17], v[74:77], v[90:93], v[2:17]
	v_mfma_f32_32x32x16_bf16 v[2:17], v[78:81], v[94:97], v[2:17]
	s_and_saveexec_b64 s[66:67], vcc
	s_cbranch_execz .LBB0_136
; template <int MODE>
; __device__ __forceinline__ void partialSM(f32x16& p0, f32x16& p1, float& m_reg, float& mn, float& alpha, int relh, int relw_min, int relw_max, const float* lut) {
;     ...
;     if (nearT) {
; #pragma unroll
;       for (int r = 0; r < 16; ++r) { const int i0 = relh + (r & 3) + 8 * (r >> 2);
;         const int a0 = min(max(i0, -129), 129) + 129, a1 = min(max(i0 + 32, -129), 129) + 129;
;         p0[r] = fmaf(p0[r], C, lut[a0]); p1[r] = fmaf(p1[r], C, lut[a1]); }
;     ...
;     float pmax = p0[0];
; #pragma unroll
;     for (int r = 1; r < 16; ++r) pmax = fmaxf(pmax, p0[r]);
; #pragma unroll
;     for (int r = 0; r < 16; ++r) pmax = fmaxf(pmax, p1[r]);
	s_cmp_gt_i32 s91, s23
	s_cselect_b64 vcc, -1, 0
	s_mov_b64 s[70:71], -1
	s_and_saveexec_b64 s[68:69], vcc
	s_cbranch_execz .LBB0_135
	v_add_u32_e32 v227, s77, v222
	v_add_u32_e32 v66, 64, v227
	v_add_u32_e32 v68, 0x41, v227
	v_add_u32_e32 v70, 0x42, v227
	v_add_u32_e32 v72, 0x43, v227
	v_med3_i32 v67, v66, s39, v198
	v_med3_i32 v66, v66, s33, v199
	v_med3_i32 v69, v68, s39, v198
	v_med3_i32 v68, v68, s33, v199
	v_med3_i32 v71, v70, s39, v198
	v_med3_i32 v70, v70, s33, v199
	v_med3_i32 v73, v72, s39, v198
	v_med3_i32 v72, v72, s33, v199
	v_lshl_add_u32 v67, v67, 2, s76
	v_lshl_add_u32 v66, v66, 2, s76
	v_lshl_add_u32 v69, v69, 2, s76
	v_lshl_add_u32 v68, v68, 2, s76
	v_lshl_add_u32 v70, v70, 2, s76
	v_lshl_add_u32 v72, v72, 2, s76
	v_lshl_add_u32 v71, v71, 2, s76
	v_lshl_add_u32 v73, v73, 2, s76
	ds_read_b32 v194, v67 offset:516
	ds_read_b32 v66, v66 offset:644
	ds_read_b32 v195, v69 offset:516
	ds_read_b32 v67, v68 offset:644
	ds_read_b32 v229, v71 offset:516
	ds_read_b32 v68, v70 offset:644
	ds_read_b32 v230, v73 offset:516
	ds_read_b32 v69, v72 offset:644
	v_add_u32_e32 v70, 0x48, v227
	v_add_u32_e32 v72, 0x49, v227
	v_add_u32_e32 v74, 0x4a, v227
	v_add_u32_e32 v76, 0x4b, v227
	v_med3_i32 v71, v70, s39, v198
	v_med3_i32 v70, v70, s33, v199
	v_med3_i32 v73, v72, s39, v198
	v_med3_i32 v72, v72, s33, v199
	v_med3_i32 v75, v74, s39, v198
	v_med3_i32 v74, v74, s33, v199
	v_med3_i32 v77, v76, s39, v198
	v_med3_i32 v76, v76, s33, v199
	v_lshl_add_u32 v71, v71, 2, s76
	v_lshl_add_u32 v70, v70, 2, s76
	v_lshl_add_u32 v73, v73, 2, s76
	v_lshl_add_u32 v72, v72, 2, s76
	v_lshl_add_u32 v74, v74, 2, s76
	v_lshl_add_u32 v76, v76, 2, s76
	v_lshl_add_u32 v75, v75, 2, s76
	v_lshl_add_u32 v77, v77, 2, s76
	ds_read_b32 v231, v71 offset:516
	ds_read_b32 v70, v70 offset:644
	ds_read_b32 v232, v73 offset:516
	ds_read_b32 v71, v72 offset:644
	ds_read_b32 v233, v75 offset:516
	ds_read_b32 v72, v74 offset:644
	ds_read_b32 v234, v77 offset:516
	ds_read_b32 v73, v76 offset:644
	v_add_u32_e32 v74, 0x50, v227
	v_add_u32_e32 v76, 0x51, v227
	v_add_u32_e32 v78, 0x52, v227
	v_add_u32_e32 v80, 0x53, v227
	v_med3_i32 v75, v74, s39, v198
	v_med3_i32 v74, v74, s33, v199
	v_med3_i32 v77, v76, s39, v198
	v_med3_i32 v76, v76, s33, v199
	v_med3_i32 v79, v78, s39, v198
	v_med3_i32 v78, v78, s33, v199
	v_med3_i32 v81, v80, s39, v198
	v_med3_i32 v80, v80, s33, v199
	v_lshl_add_u32 v75, v75, 2, s76
	v_lshl_add_u32 v74, v74, 2, s76
	v_lshl_add_u32 v77, v77, 2, s76
	v_lshl_add_u32 v76, v76, 2, s76
	v_lshl_add_u32 v78, v78, 2, s76
	v_lshl_add_u32 v80, v80, 2, s76
	v_lshl_add_u32 v79, v79, 2, s76
	v_lshl_add_u32 v81, v81, 2, s76
	ds_read_b32 v235, v75 offset:516
	ds_read_b32 v74, v74 offset:644
	ds_read_b32 v236, v77 offset:516
	ds_read_b32 v75, v76 offset:644
	ds_read_b32 v237, v79 offset:516
	ds_read_b32 v76, v78 offset:644
	ds_read_b32 v238, v81 offset:516
	ds_read_b32 v77, v80 offset:644
	v_add_u32_e32 v78, 0x58, v227
	v_add_u32_e32 v80, 0x59, v227
	v_add_u32_e32 v82, 0x5a, v227
	v_med3_i32 v79, v78, s39, v198
	v_med3_i32 v78, v78, s33, v199
	v_med3_i32 v81, v80, s39, v198
	v_med3_i32 v80, v80, s33, v199
	v_med3_i32 v83, v82, s39, v198
	v_med3_i32 v82, v82, s33, v199
	v_add_u32_e32 v84, 0x5b, v227
	s_waitcnt lgkmcnt(14)
	v_fmac_f32_e32 v194, 0x3e38aa3b, v114
	v_fmac_f32_e32 v195, 0x3e38aa3b, v115
	v_lshl_add_u32 v79, v79, 2, s76
	v_lshl_add_u32 v78, v78, 2, s76
	v_lshl_add_u32 v81, v81, 2, s76
	v_lshl_add_u32 v80, v80, 2, s76
	v_lshl_add_u32 v82, v82, 2, s76
	v_med3_i32 v85, v84, s39, v198
	v_med3_i32 v84, v84, s33, v199
	v_fmac_f32_e32 v229, 0x3e38aa3b, v116
	v_fmac_f32_e32 v230, 0x3e38aa3b, v117
	v_lshl_add_u32 v83, v83, 2, s76
	v_lshl_add_u32 v85, v85, 2, s76
	v_lshl_add_u32 v84, v84, 2, s76
	ds_read_b32 v239, v79 offset:516
	ds_read_b32 v78, v78 offset:644
	ds_read_b32 v240, v81 offset:516
	ds_read_b32 v79, v80 offset:644
	ds_read_b32 v241, v83 offset:516
	ds_read_b32 v80, v82 offset:644
	ds_read_b32 v242, v85 offset:516
	ds_read_b32 v81, v84 offset:644
	v_max_f32_e32 v82, v194, v195
	v_fmac_f32_e32 v231, 0x3e38aa3b, v118
	s_waitcnt lgkmcnt(14)
; template <int MODE>
; __device__ __forceinline__ void partialSM(f32x16& p0, f32x16& p1, float& m_reg, float& mn, float& alpha, int relh, int relw_min, int relw_max, const float* lut) {
;     ...
;     float pmax = p0[0];
; #pragma unroll
;     for (int r = 1; r < 16; ++r) pmax = fmaxf(pmax, p0[r]);
; #pragma unroll
;     for (int r = 0; r < 16; ++r) pmax = fmaxf(pmax, p1[r]);
;     { auto rr = __builtin_amdgcn_permlane32_swap(__float_as_uint(pmax), __float_as_uint(pmax), false, false);
;       pmax = fmaxf(__uint_as_float(rr[0]), __uint_as_float(rr[1])); }
;     if (__builtin_expect(__all(pmax - m_reg <= THR2), 1)) { mn = m_reg; alpha = 1.f; }
;     else { mn = fmaxf(m_reg, pmax); alpha = __builtin_amdgcn_exp2f(m_reg - mn); m_reg = mn; }
; #pragma unroll
;     for (int r = 0; r < 16; ++r) p0[r] = __builtin_amdgcn_exp2f(p0[r] - mn);
; #pragma unroll
;     for (int r = 0; r < 16; ++r) p1[r] = p1[r] - mn;
	v_fmac_f32_e32 v232, 0x3e38aa3b, v119
	v_max3_f32 v82, v82, v229, v230
	v_fmac_f32_e32 v233, 0x3e38aa3b, v120
	v_fmac_f32_e32 v234, 0x3e38aa3b, v121
	v_max3_f32 v82, v82, v231, v232
	v_fmac_f32_e32 v235, 0x3e38aa3b, v122
	s_waitcnt lgkmcnt(13)
	v_fmac_f32_e32 v236, 0x3e38aa3b, v123
	v_max3_f32 v82, v82, v233, v234
	s_waitcnt lgkmcnt(11)
	v_fmac_f32_e32 v237, 0x3e38aa3b, v124
	s_waitcnt lgkmcnt(9)
	v_fmac_f32_e32 v238, 0x3e38aa3b, v125
	v_max3_f32 v82, v82, v235, v236
	s_waitcnt lgkmcnt(7)
	v_fmac_f32_e32 v239, 0x3e38aa3b, v126
	s_waitcnt lgkmcnt(5)
	v_fmac_f32_e32 v240, 0x3e38aa3b, v127
	v_max3_f32 v82, v82, v237, v238
	s_waitcnt lgkmcnt(3)
	v_fmac_f32_e32 v241, 0x3e38aa3b, v128
	s_waitcnt lgkmcnt(1)
	v_fmac_f32_e32 v242, 0x3e38aa3b, v129
	v_max3_f32 v82, v82, v239, v240
	v_max3_f32 v84, v82, v241, v242
	v_pk_fma_f32 v[82:83], v[98:99], s[48:49], v[66:67] op_sel_hi:[1,0,1]
	v_pk_fma_f32 v[86:87], v[102:103], s[48:49], v[70:71] op_sel_hi:[1,0,1]
	v_max3_f32 v66, v84, v82, v83
	v_pk_fma_f32 v[84:85], v[100:101], s[48:49], v[68:69] op_sel_hi:[1,0,1]
	v_pk_fma_f32 v[88:89], v[104:105], s[48:49], v[72:73] op_sel_hi:[1,0,1]
	v_max3_f32 v66, v66, v84, v85
	v_max3_f32 v66, v66, v86, v87
	v_max3_f32 v66, v66, v88, v89
	v_pk_fma_f32 v[90:91], v[106:107], s[48:49], v[74:75] op_sel_hi:[1,0,1]
	v_pk_fma_f32 v[92:93], v[108:109], s[48:49], v[76:77] op_sel_hi:[1,0,1]
	v_max3_f32 v66, v66, v90, v91
	v_max3_f32 v66, v66, v92, v93
	v_pk_fma_f32 v[94:95], v[110:111], s[48:49], v[78:79] op_sel_hi:[1,0,1]
	s_waitcnt lgkmcnt(0)
	v_pk_fma_f32 v[96:97], v[112:113], s[48:49], v[80:81] op_sel_hi:[1,0,1]
	v_max3_f32 v66, v66, v94, v95
	v_max3_f32 v66, v66, v96, v97
	v_mov_b32_e32 v67, v66
	s_nop 1
	v_permlane32_swap_b32_e32 v66, v67
	v_max_f32_e32 v66, v66, v67
	v_sub_f32_e32 v67, v66, v219
	v_cmp_ge_f32_e32 vcc, s94, v67
	v_max_f32_e32 v66, v219, v66
	v_sub_f32_e32 v67, v219, v66
	v_exp_f32_e32 v67, v67
	s_cmp_eq_u64 vcc, exec
	s_cselect_b64 vcc, -1, 0
	v_cndmask_b32_e32 v228, v66, v219, vcc
	v_cndmask_b32_e64 v226, v67, 1.0, vcc
	v_sub_f32_e32 v66, v194, v228
	v_sub_f32_e32 v67, v195, v228
	v_sub_f32_e32 v68, v229, v228
	v_sub_f32_e32 v69, v230, v228
	v_sub_f32_e32 v70, v231, v228
	v_sub_f32_e32 v71, v232, v228
	v_sub_f32_e32 v72, v233, v228
	v_sub_f32_e32 v73, v234, v228
	v_sub_f32_e32 v74, v235, v228
	v_sub_f32_e32 v75, v236, v228
	v_sub_f32_e32 v76, v237, v228
	v_sub_f32_e32 v77, v238, v228
	v_sub_f32_e32 v78, v239, v228
	v_sub_f32_e32 v79, v240, v228
	v_sub_f32_e32 v80, v241, v228
	v_sub_f32_e32 v81, v242, v228
	v_exp_f32_e32 v66, v66
	v_exp_f32_e32 v67, v67
	v_exp_f32_e32 v68, v68
	v_exp_f32_e32 v69, v69
	v_exp_f32_e32 v70, v70
	v_exp_f32_e32 v71, v71
	v_exp_f32_e32 v72, v72
	v_exp_f32_e32 v73, v73
	v_exp_f32_e32 v74, v74
	v_exp_f32_e32 v75, v75
	v_exp_f32_e32 v76, v76
	v_exp_f32_e32 v77, v77
	v_exp_f32_e32 v78, v78
	v_exp_f32_e32 v79, v79
	v_exp_f32_e32 v80, v80
	v_exp_f32_e32 v81, v81
	v_sub_f32_e32 v97, v97, v228
	v_sub_f32_e32 v96, v96, v228
	v_sub_f32_e32 v95, v95, v228
	v_sub_f32_e32 v94, v94, v228
	v_sub_f32_e32 v93, v93, v228
	v_sub_f32_e32 v92, v92, v228
	v_sub_f32_e32 v91, v91, v228
	v_sub_f32_e32 v90, v90, v228
	v_sub_f32_e32 v89, v89, v228
	v_sub_f32_e32 v88, v88, v228
	v_sub_f32_e32 v87, v87, v228
	v_sub_f32_e32 v86, v86, v228
	v_sub_f32_e32 v85, v85, v228
	v_sub_f32_e32 v84, v84, v228
	v_sub_f32_e32 v83, v83, v228
	v_sub_f32_e32 v82, v82, v228
	s_xor_b64 s[70:71], exec, -1

; #define SBAR() __builtin_amdgcn_sched_barrier(0)
; #define SLOAD(i, k0) do { sr_[i].vs0 = *reinterpret_cast<const bf16x8*>(&Vh[(size_t)((k0) + sr) * LDQK + sc]); sr_[i].vs1 = *reinterpret_cast<const bf16x8*>(&Vh[(size_t)((k0) + 32 + sr) * LDQK + sc]); \
;     sr_[i].ks0 = *reinterpret_cast<const bf16x8*>(&Kh[(size_t)((k0) + sr) * LDQK + sc]); sr_[i].ks1 = *reinterpret_cast<const bf16x8*>(&Kh[(size_t)((k0) + 32 + sr) * LDQK + sc]); } while (0)
; #define SWAIT() asm volatile("s_waitcnt vmcnt(4)" ::: "memory")
; __device__ __forceinline__ void finishSM(f32x16& p0, f32x16& p1, float alpha, float& l_reg, bf16x8& pa0, bf16x8& pa1, bf16x8& pa2, bf16x8& pa3) {
; #pragma unroll
;   for (int r = 0; r < 16; ++r) p1[r] = __builtin_amdgcn_exp2f(p1[r]);
;   float ps = 0;
; #pragma unroll
;   for (int r = 0; r < 16; ++r) ps += p0[r];
; #pragma unroll
;   for (int r = 0; r < 16; ++r) ps += p1[r];
;   { auto rr = __builtin_amdgcn_permlane32_swap(__float_as_uint(ps), __float_as_uint(ps), false, false);
;     ps = __uint_as_float(rr[0]) + __uint_as_float(rr[1]); }
;   l_reg = l_reg * alpha + ps;
;     ...
;   PK4(p0, 0, pa0); PK4(p0, 8, pa1); PK4(p1, 0, pa2); PK4(p1, 8, pa3);
;     ...
; }
; template <int ND0, int DOFF>
; __device__ __forceinline__ void qkt(f32x16& p0, f32x16& p1, const char* Ks, const bf16x8* qr, int r32, int hi) {
;   p0 = f32x16{}; p1 = f32x16{};
; #pragma unroll
;   for (int d0 = 0; d0 < ND0; ++d0) { const int cb = ((d0 + DOFF) * 16 + hi * 8) * 2;
;     bf16x8 b0 = *reinterpret_cast<const bf16x8*>(Ks + KSWZ(r32, cb));
;     bf16x8 b1 = *reinterpret_cast<const bf16x8*>(Ks + KSWZ(32 + r32, cb));
;     p0 = __builtin_amdgcn_mfma_f32_32x32x16_bf16(b0, qr[d0], p0, 0, 0, 0);
;     p1 = __builtin_amdgcn_mfma_f32_32x32x16_bf16(b1, qr[d0], p1, 0, 0, 0); }
; }
; template <int MODE>
; __device__ __forceinline__ void attn_body(const bf16_t* __restrict__ Qb, const bf16_t* __restrict__ Kh, const bf16_t* __restrict__ Vh, int NT, int krel0,
;                                           char* lds, const float* __restrict__ lutg, const AttnEpi& E) {
;     ...
;     SWAIT(); SWRITE(ow, SE);
;     RESC(alB);
;     { const int t = op; op = oq; oq = ow; ow = t; }
;     __syncthreads();
;     SBAR(); qkt<ND0, DOFF>(pA0, pA1, K_lds + oq, qr, r32, hi);
;     finishSM(pB0, pB1, alB, l_reg, pa0, pa1, pa2, pa3); SBAR();
;     if (j + 3 < NT) SLOAD(SE, (j + 3) * 64); SBAR();
.LBB0_138:
	s_or_b64 exec, exec, s[66:67]
	s_add_i32 s66, s79, 0
	v_cmp_gt_f32_e32 vcc, 1.0, v226
	s_cbranch_vccz .LBB0_142
	s_and_saveexec_b64 s[64:65], s[6:7]
	ds_write_b32 v209, v226 offset:128
	s_or_b64 exec, exec, s[64:65]
	s_waitcnt lgkmcnt(0)
	ds_read_b128 v[98:101], v208 offset:224
	ds_read_b128 v[102:105], v208 offset:192
	ds_read_b128 v[106:109], v208 offset:160
	ds_read_b128 v[110:113], v208 offset:128
	s_waitcnt lgkmcnt(3)
	v_pk_mul_f32 v[64:65], v[64:65], v[100:101]
	s_waitcnt lgkmcnt(2)
	v_pk_mul_f32 v[60:61], v[60:61], v[104:105]
	s_waitcnt lgkmcnt(1)
	v_pk_mul_f32 v[56:57], v[56:57], v[108:109]
	s_waitcnt lgkmcnt(0)
	v_pk_mul_f32 v[52:53], v[52:53], v[112:113]
	v_pk_mul_f32 v[62:63], v[62:63], v[98:99]
	v_pk_mul_f32 v[58:59], v[58:59], v[102:103]
	v_pk_mul_f32 v[54:55], v[54:55], v[106:107]
	v_pk_mul_f32 v[50:51], v[50:51], v[110:111]
	v_pk_mul_f32 v[48:49], v[48:49], v[100:101]
	v_pk_mul_f32 v[44:45], v[44:45], v[104:105]
	v_pk_mul_f32 v[40:41], v[40:41], v[108:109]
	v_pk_mul_f32 v[36:37], v[36:37], v[112:113]
	v_pk_mul_f32 v[46:47], v[46:47], v[98:99]
	v_pk_mul_f32 v[42:43], v[42:43], v[102:103]
	v_pk_mul_f32 v[38:39], v[38:39], v[106:107]
	v_pk_mul_f32 v[34:35], v[34:35], v[110:111]
	v_pk_mul_f32 v[32:33], v[32:33], v[100:101]
	v_pk_mul_f32 v[28:29], v[28:29], v[104:105]
	v_pk_mul_f32 v[24:25], v[24:25], v[108:109]
	v_pk_mul_f32 v[20:21], v[20:21], v[112:113]
	v_pk_mul_f32 v[30:31], v[30:31], v[98:99]
	v_pk_mul_f32 v[26:27], v[26:27], v[102:103]
	v_pk_mul_f32 v[22:23], v[22:23], v[106:107]
	v_pk_mul_f32 v[18:19], v[18:19], v[110:111]
	v_pk_mul_f32 v[16:17], v[16:17], v[100:101]
	v_pk_mul_f32 v[12:13], v[12:13], v[104:105]
	v_pk_mul_f32 v[8:9], v[8:9], v[108:109]
	v_pk_mul_f32 v[4:5], v[4:5], v[112:113]
	v_pk_mul_f32 v[14:15], v[14:15], v[98:99]
	v_pk_mul_f32 v[10:11], v[10:11], v[102:103]
	v_pk_mul_f32 v[6:7], v[6:7], v[106:107]
	v_pk_mul_f32 v[2:3], v[2:3], v[110:111]
.LBB0_142:
	s_waitcnt vmcnt(0) lgkmcnt(0)
	s_barrier
	s_add_i32 m0, s80, s30
	s_nop 0
	global_load_lds_dwordx4 v248, s[26:27]
	s_add_i32 m0, m0, 0x400
	s_nop 0
	global_load_lds_dwordx4 v249, s[26:27]
	s_add_i32 m0, m0, 0xbc00
	s_nop 0
	global_load_lds_dwordx4 v250, s[28:29]
	s_add_i32 m0, m0, 0x400
	s_nop 0
	global_load_lds_dwordx4 v251, s[28:29]
	s_add_u32 s26, s26, 0x90000
	s_addc_u32 s27, s27, 0
	s_add_u32 s28, s28, 0x90000
	s_addc_u32 s29, s29, 0
	v_add_u32_e32 v102, s66, v213
	ds_read_b128 v[98:101], v102 offset:49152
	ds_read_b128 v[102:105], v102 offset:57344
	v_add_u32_e32 v194, s66, v214
	ds_read_b128 v[230:233], v194 offset:49152
	ds_read_b128 v[234:237], v194 offset:57344
	v_add_u32_e32 v194, s66, v215
	s_waitcnt lgkmcnt(3)
	v_mfma_f32_32x32x16_bf16 v[114:129], v[98:101], v[142:145], 0
	v_exp_f32_e32 v82, v82
	v_exp_f32_e32 v83, v83
	v_exp_f32_e32 v84, v84
	v_exp_f32_e32 v85, v85
	v_exp_f32_e32 v86, v86
	v_exp_f32_e32 v87, v87
	v_exp_f32_e32 v88, v88
	s_waitcnt lgkmcnt(2)
	v_mfma_f32_32x32x16_bf16 v[98:113], v[102:105], v[142:145], 0
	v_exp_f32_e32 v89, v89
	v_exp_f32_e32 v90, v90
	v_exp_f32_e32 v91, v91
	v_exp_f32_e32 v92, v92
	v_exp_f32_e32 v93, v93
	v_exp_f32_e32 v94, v94
	v_exp_f32_e32 v95, v95
	s_waitcnt lgkmcnt(1)
	v_mfma_f32_32x32x16_bf16 v[114:129], v[230:233], v[138:141], v[114:129]
	v_exp_f32_e32 v96, v96
	v_exp_f32_e32 v97, v97
	s_waitcnt lgkmcnt(0)
	v_mfma_f32_32x32x16_bf16 v[98:113], v[234:237], v[138:141], v[98:113]
	ds_read_b128 v[230:233], v194 offset:49152
	ds_read_b128 v[234:237], v194 offset:57344
	v_add_u32_e32 v194, s66, v216
	s_waitcnt lgkmcnt(1)
	v_mfma_f32_32x32x16_bf16 v[114:129], v[230:233], v[134:137], v[114:129]
	s_waitcnt lgkmcnt(0)
	v_mfma_f32_32x32x16_bf16 v[98:113], v[234:237], v[134:137], v[98:113]
	ds_read_b128 v[230:233], v194 offset:49152
	ds_read_b128 v[234:237], v194 offset:57344
	v_add_f32_e32 v194, v67, v66
	v_add_f32_e32 v194, v68, v194
	v_add_f32_e32 v194, v69, v194
	v_add_f32_e32 v194, v70, v194
	v_add_f32_e32 v194, v71, v194
	v_add_f32_e32 v194, v72, v194
	v_add_f32_e32 v194, v73, v194
	v_add_f32_e32 v194, v74, v194
	v_add_f32_e32 v194, v75, v194
	v_add_f32_e32 v194, v76, v194
	v_add_f32_e32 v194, v77, v194
	v_add_f32_e32 v194, v78, v194
	v_add_f32_e32 v194, v79, v194
	v_add_f32_e32 v194, v80, v194
	v_add_f32_e32 v194, v81, v194
	v_add_f32_e32 v194, v82, v194
	v_add_f32_e32 v194, v83, v194
	v_add_f32_e32 v194, v84, v194
	v_add_f32_e32 v194, v85, v194
	v_add_f32_e32 v194, v86, v194
	v_add_f32_e32 v194, v87, v194
	v_add_f32_e32 v194, v88, v194
	v_add_f32_e32 v194, v89, v194
	v_add_f32_e32 v194, v90, v194
	v_add_f32_e32 v194, v91, v194
	s_waitcnt lgkmcnt(1)
	v_mfma_f32_32x32x16_bf16 v[114:129], v[230:233], v[130:133], v[114:129]
	v_add_f32_e32 v194, v92, v194
	v_add_f32_e32 v194, v93, v194
	v_add_f32_e32 v194, v94, v194
	v_add_f32_e32 v194, v95, v194
	v_add_f32_e32 v194, v96, v194
	v_add_f32_e32 v229, v97, v194
	v_mov_b32_e32 v230, v229
	s_waitcnt lgkmcnt(0)
	v_mfma_f32_32x32x16_bf16 v[98:113], v[234:237], v[130:133], v[98:113]
	v_cvt_pk_bf16_f32 v66, v66, v67
	v_cvt_pk_bf16_f32 v67, v68, v69
	v_cvt_pk_bf16_f32 v68, v70, v71
	v_cvt_pk_bf16_f32 v69, v72, v73
	v_cvt_pk_bf16_f32 v70, v74, v75
	v_cvt_pk_bf16_f32 v71, v76, v77
	v_cvt_pk_bf16_f32 v72, v78, v79
	v_cvt_pk_bf16_f32 v73, v80, v81
	v_cvt_pk_bf16_f32 v74, v82, v83
	v_cvt_pk_bf16_f32 v75, v84, v85
	v_cvt_pk_bf16_f32 v76, v86, v87
	v_cvt_pk_bf16_f32 v77, v88, v89
	v_cvt_pk_bf16_f32 v78, v90, v91
	v_cvt_pk_bf16_f32 v79, v92, v93
	v_cvt_pk_bf16_f32 v80, v94, v95
	v_cvt_pk_bf16_f32 v81, v96, v97
	v_permlane32_swap_b32_e32 v229, v230
	v_permlane32_swap_b32_e32 v66, v68
	v_permlane32_swap_b32_e32 v67, v69
	v_permlane32_swap_b32_e32 v70, v72
	v_permlane32_swap_b32_e32 v71, v73
	v_permlane32_swap_b32_e32 v74, v76
	v_permlane32_swap_b32_e32 v75, v77
	v_permlane32_swap_b32_e32 v78, v80
	v_permlane32_swap_b32_e32 v79, v81
	s_add_i32 s81, s81, 2
	s_cmp_ge_u32 s81, s11
	s_cselect_b64 s[64:65], -1, 0

; #define SWRITE(off, i) do { *(bf16x8*)(V_lds + (off) + vst0) = sr_[i].vs0;          \
;     *(bf16x8*)(V_lds + (off) + vst1) = sr_[i].vs1; int kc = sc * 2;               \
;     *(bf16x8*)(K_lds + (off) + KSWZ(sr, kc)) = sr_[i].ks0;                       \
;     *(bf16x8*)(K_lds + (off) + KSWZ(32 + sr, kc)) = sr_[i].ks1; } while (0)
; #define SWAIT() asm volatile("s_waitcnt vmcnt(4)" ::: "memory")
; #define RESC(a) do { if (__any((a) < 1.f)) { if (hi == 0) al_l[r32] = (a); asm volatile("s_waitcnt lgkmcnt(0)" ::: "memory"); \
;     _Pragma("unroll") for (int d = 0; d < 4; ++d) _Pragma("unroll") for (int r = 0; r < 16; ++r) o[d][r] *= al_l[crow(r, hi)]; } } while (0)
; template <int MODE>
; __device__ __forceinline__ void attn_body(const bf16_t* __restrict__ Qb, const bf16_t* __restrict__ Kh, const bf16_t* __restrict__ Vh, int NT, int krel0,
;                                           char* lds, const float* __restrict__ lutg, const AttnEpi& E) {
;     ...
;     SWAIT(); SWRITE(ow, SO);
;     RESC(alA);
.LBB0_150:
	s_or_b64 exec, exec, s[68:69]
	s_add_i32 s68, s80, 0
	v_cmp_gt_f32_e32 vcc, 1.0, v225
	s_cbranch_vccz .LBB0_154
	s_and_saveexec_b64 s[66:67], s[6:7]
	ds_write_b32 v209, v225 offset:128
	s_or_b64 exec, exec, s[66:67]
	s_waitcnt lgkmcnt(0)
	ds_read_b128 v[98:101], v208 offset:224
	ds_read_b128 v[102:105], v208 offset:192
	ds_read_b128 v[106:109], v208 offset:160
	ds_read_b128 v[110:113], v208 offset:128
	s_waitcnt lgkmcnt(3)
	v_pk_mul_f32 v[64:65], v[64:65], v[100:101]
	s_waitcnt lgkmcnt(2)
	v_pk_mul_f32 v[60:61], v[60:61], v[104:105]
	s_waitcnt lgkmcnt(1)
	v_pk_mul_f32 v[56:57], v[56:57], v[108:109]
	s_waitcnt lgkmcnt(0)
	v_pk_mul_f32 v[52:53], v[52:53], v[112:113]
	v_pk_mul_f32 v[62:63], v[62:63], v[98:99]
	v_pk_mul_f32 v[58:59], v[58:59], v[102:103]
	v_pk_mul_f32 v[54:55], v[54:55], v[106:107]
	v_pk_mul_f32 v[50:51], v[50:51], v[110:111]
	v_pk_mul_f32 v[48:49], v[48:49], v[100:101]
	v_pk_mul_f32 v[44:45], v[44:45], v[104:105]
	v_pk_mul_f32 v[40:41], v[40:41], v[108:109]
	v_pk_mul_f32 v[36:37], v[36:37], v[112:113]
	v_pk_mul_f32 v[46:47], v[46:47], v[98:99]
	v_pk_mul_f32 v[42:43], v[42:43], v[102:103]
	v_pk_mul_f32 v[38:39], v[38:39], v[106:107]
	v_pk_mul_f32 v[34:35], v[34:35], v[110:111]
	v_pk_mul_f32 v[32:33], v[32:33], v[100:101]
	v_pk_mul_f32 v[28:29], v[28:29], v[104:105]
	v_pk_mul_f32 v[24:25], v[24:25], v[108:109]
	v_pk_mul_f32 v[20:21], v[20:21], v[112:113]
	v_pk_mul_f32 v[30:31], v[30:31], v[98:99]
	v_pk_mul_f32 v[26:27], v[26:27], v[102:103]
	v_pk_mul_f32 v[22:23], v[22:23], v[106:107]
	v_pk_mul_f32 v[18:19], v[18:19], v[110:111]
	v_pk_mul_f32 v[16:17], v[16:17], v[100:101]
	v_pk_mul_f32 v[12:13], v[12:13], v[104:105]
	v_pk_mul_f32 v[8:9], v[8:9], v[108:109]
	v_pk_mul_f32 v[4:5], v[4:5], v[112:113]
	v_pk_mul_f32 v[14:15], v[14:15], v[98:99]
	v_pk_mul_f32 v[10:11], v[10:11], v[102:103]
	v_pk_mul_f32 v[6:7], v[6:7], v[106:107]
	v_pk_mul_f32 v[2:3], v[2:3], v[110:111]

; #define SBAR() __builtin_amdgcn_sched_barrier(0)
; __device__ __forceinline__ void finishSM(f32x16& p0, f32x16& p1, float alpha, float& l_reg, bf16x8& pa0, bf16x8& pa1, bf16x8& pa2, bf16x8& pa3) {
; #pragma unroll
;   for (int r = 0; r < 16; ++r) p1[r] = __builtin_amdgcn_exp2f(p1[r]);
;   float ps = 0;
; #pragma unroll
;   for (int r = 0; r < 16; ++r) ps += p0[r];
; #pragma unroll
;   for (int r = 0; r < 16; ++r) ps += p1[r];
;   { auto rr = __builtin_amdgcn_permlane32_swap(__float_as_uint(ps), __float_as_uint(ps), false, false);
;     ps = __uint_as_float(rr[0]) + __uint_as_float(rr[1]); }
;   l_reg = l_reg * alpha + ps;
;     ...
;   PK4(p0, 0, pa0); PK4(p0, 8, pa1); PK4(p1, 0, pa2); PK4(p1, 8, pa3);
;     ...
; }
; template <int ND0, int DOFF>
; __device__ __forceinline__ void qkt(f32x16& p0, f32x16& p1, const char* Ks, const bf16x8* qr, int r32, int hi) {
;   p0 = f32x16{}; p1 = f32x16{};
; #pragma unroll
;   for (int d0 = 0; d0 < ND0; ++d0) { const int cb = ((d0 + DOFF) * 16 + hi * 8) * 2;
;     bf16x8 b0 = *reinterpret_cast<const bf16x8*>(Ks + KSWZ(r32, cb));
;     bf16x8 b1 = *reinterpret_cast<const bf16x8*>(Ks + KSWZ(32 + r32, cb));
;     p0 = __builtin_amdgcn_mfma_f32_32x32x16_bf16(b0, qr[d0], p0, 0, 0, 0);
;     p1 = __builtin_amdgcn_mfma_f32_32x32x16_bf16(b1, qr[d0], p1, 0, 0, 0); }
; }
; __device__ __forceinline__ int v_st(int k, int c) { const int kk = (k & ~0xC) | ((k & 4) << 1) | ((k & 8) >> 1); return ((kk >> 3) * 4 + (c >> 5)) * 512 + ((kk & 7) * 32 + (c & 31)) * 2; }
; __device__ __forceinline__ int v_rd_base(int lane) { return ((lane & 3) << 3) | (((lane >> 2) & 3) << 6) | (((lane >> 4) & 1) << 5) | (((lane >> 5) & 1) << 8); }
; template <int OFF> __device__ __forceinline__ s16x4 tr_read(int vb) {
;   s16x4 r; asm volatile("ds_read_b64_tr_b16 %0, %1 offset:%2" : "=&v"(r) : "v"(vb), "i"(OFF) : "memory"); return r;
; }
; template <int MODE>
; __device__ __forceinline__ void attn_body(const bf16_t* __restrict__ Qb, const bf16_t* __restrict__ Kh, const bf16_t* __restrict__ Vh, int NT, int krel0,
;                                           char* lds, const float* __restrict__ lutg, const AttnEpi& E) {
;     ...
;   __syncthreads();
;   SBAR(); qkt<ND0, DOFF>(pB0, pB1, K_lds + oq, qr, r32, hi);
;   finishSM(pA0, pA1, alA, l_reg, pa0, pa1, pa2, pa3); SBAR();
;   pv_d0(o, vb0 + op, pa0, pa1, pa2, pa3); PSM(pB0, pB1, mnB, alB, NT - 1);
.LBB0_156:
	s_waitcnt vmcnt(0) lgkmcnt(0)
	s_barrier
	v_add_u32_e32 v102, s68, v213
	ds_read_b128 v[98:101], v102 offset:49152
	ds_read_b128 v[102:105], v102 offset:57344
	v_add_u32_e32 v146, s68, v214
	v_exp_f32_e32 v82, v82
	v_exp_f32_e32 v83, v83
	s_waitcnt lgkmcnt(1)
	v_mfma_f32_32x32x16_bf16 v[114:129], v[98:101], v[142:145], 0
	v_exp_f32_e32 v84, v84
	v_exp_f32_e32 v85, v85
	v_exp_f32_e32 v86, v86
	v_exp_f32_e32 v87, v87
	v_exp_f32_e32 v88, v88
	v_exp_f32_e32 v89, v89
	v_exp_f32_e32 v90, v90
	s_waitcnt lgkmcnt(0)
	v_mfma_f32_32x32x16_bf16 v[98:113], v[102:105], v[142:145], 0
	ds_read_b128 v[142:145], v146 offset:49152
	ds_read_b128 v[146:149], v146 offset:57344
	v_exp_f32_e32 v91, v91
	v_exp_f32_e32 v92, v92
	v_exp_f32_e32 v93, v93
	v_exp_f32_e32 v94, v94
	v_exp_f32_e32 v95, v95
	v_exp_f32_e32 v96, v96
	s_waitcnt lgkmcnt(1)
	v_mfma_f32_32x32x16_bf16 v[114:129], v[142:145], v[138:141], v[114:129]
	v_add_u32_e32 v142, s68, v215
	v_exp_f32_e32 v97, v97
	s_waitcnt lgkmcnt(0)
	v_mfma_f32_32x32x16_bf16 v[98:113], v[146:149], v[138:141], v[98:113]
	ds_read_b128 v[138:141], v142 offset:49152
	ds_read_b128 v[142:145], v142 offset:57344
	s_waitcnt lgkmcnt(1)
	v_mfma_f32_32x32x16_bf16 v[114:129], v[138:141], v[134:137], v[114:129]
	v_add_u32_e32 v138, s68, v216
	s_waitcnt lgkmcnt(0)
	v_mfma_f32_32x32x16_bf16 v[98:113], v[142:145], v[134:137], v[98:113]
	ds_read_b128 v[134:137], v138 offset:49152
	ds_read_b128 v[138:141], v138 offset:57344
	s_waitcnt lgkmcnt(1)
	v_mfma_f32_32x32x16_bf16 v[114:129], v[134:137], v[130:133], v[114:129]
	s_waitcnt lgkmcnt(0)
	v_mfma_f32_32x32x16_bf16 v[98:113], v[138:141], v[130:133], v[98:113]
	v_add_f32_e32 v130, 0, v66
	v_add_f32_e32 v130, v67, v130
	v_add_f32_e32 v130, v68, v130
	v_add_f32_e32 v130, v69, v130
	v_add_f32_e32 v130, v70, v130
	v_add_f32_e32 v130, v71, v130
	v_add_f32_e32 v130, v72, v130
	v_add_f32_e32 v130, v73, v130
	v_add_f32_e32 v130, v74, v130
	v_add_f32_e32 v130, v75, v130
	v_add_f32_e32 v130, v76, v130
	v_add_f32_e32 v130, v77, v130
	v_add_f32_e32 v130, v78, v130
	v_add_f32_e32 v130, v79, v130
	v_add_f32_e32 v130, v80, v130
	v_add_f32_e32 v130, v81, v130
	v_add_f32_e32 v130, v82, v130
	v_add_f32_e32 v130, v83, v130
	v_add_f32_e32 v130, v84, v130
	v_add_f32_e32 v130, v85, v130
	v_add_f32_e32 v130, v86, v130
	v_add_f32_e32 v130, v87, v130
	v_add_f32_e32 v130, v88, v130
	v_add_f32_e32 v130, v89, v130
	v_add_f32_e32 v130, v90, v130
	v_add_f32_e32 v130, v91, v130
	v_add_f32_e32 v130, v92, v130
	v_add_f32_e32 v130, v93, v130
	v_add_f32_e32 v130, v94, v130
	v_add_f32_e32 v130, v95, v130
	v_add_f32_e32 v130, v96, v130
	v_add_f32_e32 v130, v97, v130
	v_mov_b32_e32 v131, v130
	v_cvt_pk_bf16_f32 v66, v66, v67
	v_cvt_pk_bf16_f32 v67, v68, v69
	v_cvt_pk_bf16_f32 v68, v70, v71
	v_cvt_pk_bf16_f32 v69, v72, v73
	v_cvt_pk_bf16_f32 v70, v74, v75
	v_cvt_pk_bf16_f32 v71, v76, v77
	v_cvt_pk_bf16_f32 v72, v78, v79
	v_cvt_pk_bf16_f32 v73, v80, v81
	v_cvt_pk_bf16_f32 v74, v82, v83
	v_cvt_pk_bf16_f32 v75, v84, v85
	v_cvt_pk_bf16_f32 v76, v86, v87
	v_cvt_pk_bf16_f32 v77, v88, v89
	v_cvt_pk_bf16_f32 v78, v90, v91
	v_cvt_pk_bf16_f32 v79, v92, v93
	v_cvt_pk_bf16_f32 v80, v94, v95
	v_cvt_pk_bf16_f32 v81, v96, v97
	v_permlane32_swap_b32_e32 v130, v131
	v_permlane32_swap_b32_e32 v66, v68
	v_permlane32_swap_b32_e32 v67, v69
	v_permlane32_swap_b32_e32 v70, v72
	v_permlane32_swap_b32_e32 v71, v73
	v_permlane32_swap_b32_e32 v74, v76
	v_permlane32_swap_b32_e32 v75, v77
	v_permlane32_swap_b32_e32 v78, v80
	v_permlane32_swap_b32_e32 v79, v81
	v_add_u32_e32 v132, s79, v218
	ds_read_b64_tr_b16 v[82:83], v132 offset:0
	ds_read_b64_tr_b16 v[84:85], v132 offset:0x800
	ds_read_b64_tr_b16 v[86:87], v132 offset:0x1000
	ds_read_b64_tr_b16 v[88:89], v132 offset:0x1800
	ds_read_b64_tr_b16 v[90:91], v132 offset:0x2000
	ds_read_b64_tr_b16 v[92:93], v132 offset:0x2800
	ds_read_b64_tr_b16 v[94:95], v132 offset:0x3000
	ds_read_b64_tr_b16 v[96:97], v132 offset:0x3800
	s_waitcnt lgkmcnt(0)
	s_nop 0
	v_mfma_f32_32x32x16_bf16 v[50:65], v[66:69], v[82:85], v[50:65]
	ds_read_b64_tr_b16 v[82:83], v132 offset:0x200
	ds_read_b64_tr_b16 v[84:85], v132 offset:0xa00
	v_mfma_f32_32x32x16_bf16 v[50:65], v[70:73], v[86:89], v[50:65]
	ds_read_b64_tr_b16 v[86:87], v132 offset:0x1200
	ds_read_b64_tr_b16 v[88:89], v132 offset:0x1a00
	v_mfma_f32_32x32x16_bf16 v[50:65], v[74:77], v[90:93], v[50:65]
	ds_read_b64_tr_b16 v[90:91], v132 offset:0x2200
	ds_read_b64_tr_b16 v[92:93], v132 offset:0x2a00
	v_mfma_f32_32x32x16_bf16 v[50:65], v[78:81], v[94:97], v[50:65]
	ds_read_b64_tr_b16 v[94:95], v132 offset:0x3200
	ds_read_b64_tr_b16 v[96:97], v132 offset:0x3a00
	s_waitcnt lgkmcnt(0)
	v_mfma_f32_32x32x16_bf16 v[34:49], v[66:69], v[82:85], v[34:49]
	ds_read_b64_tr_b16 v[82:83], v132 offset:0x400
	ds_read_b64_tr_b16 v[84:85], v132 offset:0xc00
	v_mfma_f32_32x32x16_bf16 v[34:49], v[70:73], v[86:89], v[34:49]
	ds_read_b64_tr_b16 v[86:87], v132 offset:0x1400
	ds_read_b64_tr_b16 v[88:89], v132 offset:0x1c00
	v_mfma_f32_32x32x16_bf16 v[34:49], v[74:77], v[90:93], v[34:49]
	ds_read_b64_tr_b16 v[90:91], v132 offset:0x2400
	ds_read_b64_tr_b16 v[92:93], v132 offset:0x2c00
	v_mfma_f32_32x32x16_bf16 v[34:49], v[78:81], v[94:97], v[34:49]
	ds_read_b64_tr_b16 v[94:95], v132 offset:0x3400
	ds_read_b64_tr_b16 v[96:97], v132 offset:0x3c00
	s_waitcnt lgkmcnt(0)
	v_mfma_f32_32x32x16_bf16 v[18:33], v[66:69], v[82:85], v[18:33]
	ds_read_b64_tr_b16 v[82:83], v132 offset:0x600
	ds_read_b64_tr_b16 v[84:85], v132 offset:0xe00
	v_mfma_f32_32x32x16_bf16 v[18:33], v[70:73], v[86:89], v[18:33]
	ds_read_b64_tr_b16 v[86:87], v132 offset:0x1600
	ds_read_b64_tr_b16 v[88:89], v132 offset:0x1e00
	v_mfma_f32_32x32x16_bf16 v[18:33], v[74:77], v[90:93], v[18:33]
	ds_read_b64_tr_b16 v[90:91], v132 offset:0x2600
	ds_read_b64_tr_b16 v[92:93], v132 offset:0x2e00
	v_mfma_f32_32x32x16_bf16 v[18:33], v[78:81], v[94:97], v[18:33]
	ds_read_b64_tr_b16 v[94:95], v132 offset:0x3600
	ds_read_b64_tr_b16 v[96:97], v132 offset:0x3e00
	s_waitcnt lgkmcnt(0)
	v_mfma_f32_32x32x16_bf16 v[2:17], v[66:69], v[82:85], v[2:17]
	s_lshl_b32 s64, s11, 6
	s_sub_i32 s72, s64, 64
	v_add_u32_e32 v66, s72, v205
	v_cmp_gt_i32_e64 s[64:65], s95, v66
	v_cmp_lt_i32_e32 vcc, s15, v66
	v_mov_b32_e32 v133, s76
	v_mfma_f32_32x32x16_bf16 v[2:17], v[70:73], v[86:89], v[2:17]
	v_mfma_f32_32x32x16_bf16 v[2:17], v[74:77], v[90:93], v[2:17]
	v_mfma_f32_32x32x16_bf16 v[2:17], v[78:81], v[94:97], v[2:17]
	s_and_saveexec_b64 s[66:67], vcc
	v_readlane_b32 s79, v254, 57
	s_cbranch_execz .LBB0_160
; template <int MODE>
; __device__ __forceinline__ void partialSM(f32x16& p0, f32x16& p1, float& m_reg, float& mn, float& alpha, int relh, int relw_min, int relw_max, const float* lut) {
;     ...
;     if (nearT) {
; #pragma unroll
;       for (int r = 0; r < 16; ++r) { const int i0 = relh + (r & 3) + 8 * (r >> 2);
;         const int a0 = min(max(i0, -129), 129) + 129, a1 = min(max(i0 + 32, -129), 129) + 129;
;         p0[r] = fmaf(p0[r], C, lut[a0]); p1[r] = fmaf(p1[r], C, lut[a1]); }
	v_add_u32_e32 v66, s72, v204
	v_cmp_gt_i32_e32 vcc, s91, v66
	s_mov_b64 s[70:71], -1
	s_and_saveexec_b64 s[68:69], vcc
	s_cbranch_execz .LBB0_159
	v_add_u32_e32 v78, s72, v184
	v_add_u32_e32 v68, 1, v78
	v_add_u32_e32 v70, 2, v78
	v_add_u32_e32 v72, 3, v78
	v_med3_i32 v66, v78, s39, v198
	v_med3_i32 v67, v78, s33, v199
	v_med3_i32 v69, v68, s39, v198
	v_med3_i32 v68, v68, s33, v199
	v_med3_i32 v71, v70, s39, v198
	v_med3_i32 v70, v70, s33, v199
	v_med3_i32 v73, v72, s39, v198
	v_med3_i32 v72, v72, s33, v199
	v_lshl_add_u32 v66, v66, 2, s76
	v_lshl_add_u32 v67, v67, 2, s76
	v_lshl_add_u32 v69, v69, 2, s76
	v_lshl_add_u32 v68, v68, 2, s76
	v_lshl_add_u32 v70, v70, 2, s76
	v_lshl_add_u32 v72, v72, 2, s76
	v_lshl_add_u32 v71, v71, 2, s76
	v_lshl_add_u32 v73, v73, 2, s76
	ds_read_b32 v133, v66 offset:516
	ds_read_b32 v66, v67 offset:644
	ds_read_b32 v134, v69 offset:516
	ds_read_b32 v67, v68 offset:644
	ds_read_b32 v135, v71 offset:516
	ds_read_b32 v68, v70 offset:644
	ds_read_b32 v136, v73 offset:516
	ds_read_b32 v69, v72 offset:644
	v_add_u32_e32 v70, 8, v78
	v_add_u32_e32 v72, 9, v78
	v_add_u32_e32 v74, 10, v78
	v_add_u32_e32 v76, 11, v78
	v_med3_i32 v71, v70, s39, v198
	v_med3_i32 v70, v70, s33, v199
	v_med3_i32 v73, v72, s39, v198
	v_med3_i32 v72, v72, s33, v199
	v_med3_i32 v75, v74, s39, v198
	v_med3_i32 v74, v74, s33, v199
	v_med3_i32 v77, v76, s39, v198
	v_med3_i32 v76, v76, s33, v199
	v_lshl_add_u32 v71, v71, 2, s76
	v_lshl_add_u32 v70, v70, 2, s76
	v_lshl_add_u32 v73, v73, 2, s76
	v_lshl_add_u32 v72, v72, 2, s76
	v_lshl_add_u32 v74, v74, 2, s76
	v_lshl_add_u32 v76, v76, 2, s76
	v_lshl_add_u32 v75, v75, 2, s76
	v_lshl_add_u32 v77, v77, 2, s76
	ds_read_b32 v137, v71 offset:516
	ds_read_b32 v70, v70 offset:644
	ds_read_b32 v138, v73 offset:516
	ds_read_b32 v71, v72 offset:644
	ds_read_b32 v139, v75 offset:516
	ds_read_b32 v72, v74 offset:644
	ds_read_b32 v140, v77 offset:516
	ds_read_b32 v73, v76 offset:644
	v_add_u32_e32 v74, 16, v78
	v_add_u32_e32 v76, 17, v78
	v_add_u32_e32 v79, 18, v78
	v_add_u32_e32 v81, 19, v78
	v_med3_i32 v75, v74, s39, v198
	v_med3_i32 v74, v74, s33, v199
	v_med3_i32 v77, v76, s39, v198
	v_med3_i32 v76, v76, s33, v199
	v_med3_i32 v80, v79, s39, v198
	v_med3_i32 v79, v79, s33, v199
	v_med3_i32 v82, v81, s39, v198
	v_med3_i32 v81, v81, s33, v199
	v_lshl_add_u32 v75, v75, 2, s76
	v_lshl_add_u32 v74, v74, 2, s76
	v_lshl_add_u32 v77, v77, 2, s76
	v_lshl_add_u32 v76, v76, 2, s76
	v_lshl_add_u32 v79, v79, 2, s76
	v_lshl_add_u32 v81, v81, 2, s76
	v_lshl_add_u32 v80, v80, 2, s76
	v_lshl_add_u32 v82, v82, 2, s76
	ds_read_b32 v141, v75 offset:516
	ds_read_b32 v74, v74 offset:644
	ds_read_b32 v142, v77 offset:516
	ds_read_b32 v75, v76 offset:644
	ds_read_b32 v143, v80 offset:516
	ds_read_b32 v76, v79 offset:644
	ds_read_b32 v144, v82 offset:516
	ds_read_b32 v77, v81 offset:644
	v_add_u32_e32 v79, 24, v78
	v_add_u32_e32 v81, 25, v78
	v_med3_i32 v80, v79, s39, v198
	v_med3_i32 v79, v79, s33, v199
	v_med3_i32 v82, v81, s39, v198
	v_med3_i32 v81, v81, s33, v199
	v_add_u32_e32 v83, 26, v78
	v_add_u32_e32 v78, 27, v78
	s_waitcnt lgkmcnt(14)
	v_fmac_f32_e32 v133, 0x3e38aa3b, v114
	v_fmac_f32_e32 v134, 0x3e38aa3b, v115
	v_lshl_add_u32 v80, v80, 2, s76
	v_lshl_add_u32 v79, v79, 2, s76
	v_lshl_add_u32 v82, v82, 2, s76
	v_lshl_add_u32 v81, v81, 2, s76
	v_med3_i32 v84, v83, s39, v198
	v_med3_i32 v83, v83, s33, v199
	v_med3_i32 v85, v78, s39, v198
	v_med3_i32 v78, v78, s33, v199
	v_fmac_f32_e32 v135, 0x3e38aa3b, v116
	v_fmac_f32_e32 v136, 0x3e38aa3b, v117
	v_lshl_add_u32 v84, v84, 2, s76
	v_lshl_add_u32 v83, v83, 2, s76
	v_lshl_add_u32 v85, v85, 2, s76
	v_lshl_add_u32 v86, v78, 2, s76
	ds_read_b32 v145, v80 offset:516
	ds_read_b32 v78, v79 offset:644
	ds_read_b32 v146, v82 offset:516
	ds_read_b32 v79, v81 offset:644
	ds_read_b32 v147, v84 offset:516
	ds_read_b32 v80, v83 offset:644
	ds_read_b32 v148, v85 offset:516
	ds_read_b32 v81, v86 offset:644
	v_max_f32_e32 v82, v133, v134
	v_fmac_f32_e32 v137, 0x3e38aa3b, v118
	s_waitcnt lgkmcnt(14)
; template <int MODE>
; __device__ __forceinline__ void partialSM(f32x16& p0, f32x16& p1, float& m_reg, float& mn, float& alpha, int relh, int relw_min, int relw_max, const float* lut) {
;     ...
;     float pmax = p0[0];
; #pragma unroll
;     for (int r = 1; r < 16; ++r) pmax = fmaxf(pmax, p0[r]);
; #pragma unroll
;     for (int r = 0; r < 16; ++r) pmax = fmaxf(pmax, p1[r]);
;     { auto rr = __builtin_amdgcn_permlane32_swap(__float_as_uint(pmax), __float_as_uint(pmax), false, false);
;       pmax = fmaxf(__uint_as_float(rr[0]), __uint_as_float(rr[1])); }
;     if (__builtin_expect(__all(pmax - m_reg <= THR2), 1)) { mn = m_reg; alpha = 1.f; }
;     else { mn = fmaxf(m_reg, pmax); alpha = __builtin_amdgcn_exp2f(m_reg - mn); m_reg = mn; }
; #pragma unroll
;     for (int r = 0; r < 16; ++r) p0[r] = __builtin_amdgcn_exp2f(p0[r] - mn);
; #pragma unroll
;     for (int r = 0; r < 16; ++r) p1[r] = p1[r] - mn;
	v_fmac_f32_e32 v138, 0x3e38aa3b, v119
	v_max3_f32 v82, v82, v135, v136
	v_fmac_f32_e32 v139, 0x3e38aa3b, v120
	v_fmac_f32_e32 v140, 0x3e38aa3b, v121
	v_max3_f32 v82, v82, v137, v138
	v_fmac_f32_e32 v141, 0x3e38aa3b, v122
	s_waitcnt lgkmcnt(13)
	v_fmac_f32_e32 v142, 0x3e38aa3b, v123
	v_max3_f32 v82, v82, v139, v140
	s_waitcnt lgkmcnt(11)
	v_fmac_f32_e32 v143, 0x3e38aa3b, v124
	s_waitcnt lgkmcnt(9)
	v_fmac_f32_e32 v144, 0x3e38aa3b, v125
	v_max3_f32 v82, v82, v141, v142
	s_waitcnt lgkmcnt(7)
	v_fmac_f32_e32 v145, 0x3e38aa3b, v126
	s_waitcnt lgkmcnt(5)
	v_fmac_f32_e32 v146, 0x3e38aa3b, v127
	v_max3_f32 v82, v82, v143, v144
	s_waitcnt lgkmcnt(3)
	v_fmac_f32_e32 v147, 0x3e38aa3b, v128
	s_waitcnt lgkmcnt(1)
	v_fmac_f32_e32 v148, 0x3e38aa3b, v129
	v_max3_f32 v82, v82, v145, v146
	v_max3_f32 v84, v82, v147, v148
	v_pk_fma_f32 v[82:83], v[98:99], s[48:49], v[66:67] op_sel_hi:[1,0,1]
	v_pk_fma_f32 v[86:87], v[102:103], s[48:49], v[70:71] op_sel_hi:[1,0,1]
	v_max3_f32 v66, v84, v82, v83
	v_pk_fma_f32 v[84:85], v[100:101], s[48:49], v[68:69] op_sel_hi:[1,0,1]
	v_pk_fma_f32 v[88:89], v[104:105], s[48:49], v[72:73] op_sel_hi:[1,0,1]
	v_max3_f32 v66, v66, v84, v85
	v_max3_f32 v66, v66, v86, v87
	v_max3_f32 v66, v66, v88, v89
	v_pk_fma_f32 v[90:91], v[106:107], s[48:49], v[74:75] op_sel_hi:[1,0,1]
	v_pk_fma_f32 v[92:93], v[108:109], s[48:49], v[76:77] op_sel_hi:[1,0,1]
	v_max3_f32 v66, v66, v90, v91
	v_max3_f32 v66, v66, v92, v93
	v_pk_fma_f32 v[94:95], v[110:111], s[48:49], v[78:79] op_sel_hi:[1,0,1]
	s_waitcnt lgkmcnt(0)
	v_pk_fma_f32 v[96:97], v[112:113], s[48:49], v[80:81] op_sel_hi:[1,0,1]
	v_max3_f32 v66, v66, v94, v95
	v_max3_f32 v66, v66, v96, v97
	v_mov_b32_e32 v67, v66
	s_nop 1
	v_permlane32_swap_b32_e32 v66, v67
	v_max_f32_e32 v67, v67, v67
	v_max_f32_e32 v66, v66, v66
	v_max_f32_e32 v66, v66, v67
	v_sub_f32_e32 v67, v66, v219
	v_cmp_ge_f32_e32 vcc, s94, v67
	v_max_f32_e32 v67, v219, v219
	v_max_f32_e32 v66, v67, v66
	v_sub_f32_e32 v67, v219, v66
	v_exp_f32_e32 v67, v67
	s_cmp_eq_u64 vcc, exec
	s_cselect_b64 vcc, -1, 0
	v_cndmask_b32_e32 v149, v66, v219, vcc
	v_cndmask_b32_e64 v132, v67, 1.0, vcc
	v_sub_f32_e32 v66, v133, v149
	v_sub_f32_e32 v67, v134, v149
	v_sub_f32_e32 v68, v135, v149
	v_sub_f32_e32 v69, v136, v149
	v_sub_f32_e32 v70, v137, v149
	v_sub_f32_e32 v71, v138, v149
	v_sub_f32_e32 v72, v139, v149
	v_sub_f32_e32 v73, v140, v149
	v_sub_f32_e32 v74, v141, v149
	v_sub_f32_e32 v75, v142, v149
	v_sub_f32_e32 v76, v143, v149
	v_sub_f32_e32 v77, v144, v149
	v_sub_f32_e32 v78, v145, v149
	v_sub_f32_e32 v79, v146, v149
	v_sub_f32_e32 v80, v147, v149
	v_sub_f32_e32 v81, v148, v149
	v_exp_f32_e32 v66, v66
	v_exp_f32_e32 v67, v67
	v_exp_f32_e32 v68, v68
	v_exp_f32_e32 v69, v69
	v_exp_f32_e32 v70, v70
	v_exp_f32_e32 v71, v71
	v_exp_f32_e32 v72, v72
	v_exp_f32_e32 v73, v73
	v_exp_f32_e32 v74, v74
	v_exp_f32_e32 v75, v75
	v_exp_f32_e32 v76, v76
	v_exp_f32_e32 v77, v77
	v_exp_f32_e32 v78, v78
	v_exp_f32_e32 v79, v79
	v_exp_f32_e32 v80, v80
	v_exp_f32_e32 v81, v81
	v_sub_f32_e32 v97, v97, v149
	v_sub_f32_e32 v96, v96, v149
	v_sub_f32_e32 v95, v95, v149
	v_sub_f32_e32 v94, v94, v149
	v_sub_f32_e32 v93, v93, v149
	v_sub_f32_e32 v92, v92, v149
	v_sub_f32_e32 v91, v91, v149
	v_sub_f32_e32 v90, v90, v149
	v_sub_f32_e32 v89, v89, v149
	v_sub_f32_e32 v88, v88, v149
	v_sub_f32_e32 v87, v87, v149
	v_sub_f32_e32 v86, v86, v149
	v_sub_f32_e32 v85, v85, v149
	v_sub_f32_e32 v84, v84, v149
	v_sub_f32_e32 v83, v83, v149
	v_sub_f32_e32 v82, v82, v149
	s_xor_b64 s[70:71], exec, -1

; __device__ __forceinline__ int v_st(int k, int c) { const int kk = (k & ~0xC) | ((k & 4) << 1) | ((k & 8) >> 1); return ((kk >> 3) * 4 + (c >> 5)) * 512 + ((kk & 7) * 32 + (c & 31)) * 2; }
; __device__ __forceinline__ int v_rd_base(int lane) { return ((lane & 3) << 3) | (((lane >> 2) & 3) << 6) | (((lane >> 4) & 1) << 5) | (((lane >> 5) & 1) << 8); }
; #define SLOAD(i, k0) do { sr_[i].vs0 = *reinterpret_cast<const bf16x8*>(&Vh[(size_t)((k0) + sr) * LDQK + sc]); sr_[i].vs1 = *reinterpret_cast<const bf16x8*>(&Vh[(size_t)((k0) + 32 + sr) * LDQK + sc]); \
;     sr_[i].ks0 = *reinterpret_cast<const bf16x8*>(&Kh[(size_t)((k0) + sr) * LDQK + sc]); sr_[i].ks1 = *reinterpret_cast<const bf16x8*>(&Kh[(size_t)((k0) + 32 + sr) * LDQK + sc]); } while (0)
; #define SWRITE(off, i) do { *(bf16x8*)(V_lds + (off) + vst0) = sr_[i].vs0;          \
;     *(bf16x8*)(V_lds + (off) + vst1) = sr_[i].vs1; int kc = sc * 2;               \
;     *(bf16x8*)(K_lds + (off) + KSWZ(sr, kc)) = sr_[i].ks0;                       \
;     *(bf16x8*)(K_lds + (off) + KSWZ(32 + sr, kc)) = sr_[i].ks1; } while (0)
; #define SWAIT() asm volatile("s_waitcnt vmcnt(4)" ::: "memory")
; #define PSM(P0, P1, MN, AL, J) partialSM<MODE>(P0, P1, m_reg, MN, AL, relq + 64 * (J), relwmin + 64 * (J), relwmax + 64 * (J), lut)
; template <int MODE>
; __device__ __forceinline__ void attn_body(const bf16_t* __restrict__ Qb, const bf16_t* __restrict__ Kh, const bf16_t* __restrict__ Vh, int NT, int krel0,
;                                           char* lds, const float* __restrict__ lutg, const AttnEpi& E) {
;     ...
;   const int sr = tid >> 4, sc = (tid & 15) * 8, vst0 = v_st(sr, sc), vst1 = v_st(32 + sr, sc);
;   const int vb0 = (int)(uintptr_t)V_lds + v_rd_base(lane);
;   struct { bf16x8 vs0, vs1, ks0, ks1; } sr_[2];
;     ...
;   const int relq = krel0 - (wid * 32 + r32) + 4 * hi, relwmin = krel0 - (wid * 32 + 31), relwmax = krel0 + 63 - wid * 32;
;     ...
;   f32x16 pA0, pA1, pB0, pB1; float mnA, mnB, alA, alB; bf16x8 pa0, pa1, pa2, pa3;
;   constexpr int SE = 0, SO = 1;
;   SLOAD(SE, 0); SLOAD(SO, 64); asm volatile("s_waitcnt vmcnt(4)" ::: "memory"); SWRITE(0, SE); __syncthreads();
;   qkt<ND0, DOFF>(pA0, pA1, K_lds, qr, r32, hi); PSM(pA0, pA1, mnA, alA, 0);
;   if (2 < NT) SLOAD(SE, 2 * 64);
;   SWAIT(); SWRITE(SHM_V, SO);
;   int op = 0, oq = SHM_V, ow = 2 * SHM_V;
.LBB0_176:
	s_or_b64 exec, exec, s[60:61]
	v_add_u32_e32 v0, 0xa0, v50
	s_movk_i32 s60, 0x1200
	s_nop 3
	v_mad_i64_i32 v[2:3], s[6:7], v0, s60, 0
	v_add_u32_e32 v0, 0x80, v50
	v_or_b32_e32 v2, v2, v51
	v_mad_i64_i32 v[6:7], s[6:7], v0, s60, 0
	v_lshlrev_b64 v[2:3], 1, v[2:3]
	v_or_b32_e32 v6, v6, v51
	v_lshl_add_u64 v[4:5], s[58:59], 0, v[2:3]
	v_lshlrev_b64 v[6:7], 1, v[6:7]
	v_lshl_add_u64 v[2:3], s[0:1], 0, v[2:3]
	v_lshl_add_u64 v[8:9], s[58:59], 0, v[6:7]
	global_load_dwordx4 v[150:153], v[4:5], off
	global_load_dwordx4 v[146:149], v[8:9], off
	v_lshl_add_u64 v[4:5], s[0:1], 0, v[6:7]
	global_load_dwordx4 v[158:161], v[2:3], off
	global_load_dwordx4 v[154:157], v[4:5], off
	v_and_b32_e32 v0, 63, v188
	v_lshlrev_b32_e32 v3, 4, v0
	v_lshlrev_b32_e32 v2, 3, v0
	v_and_b32_e32 v3, 0xc0, v3
	v_lshlrev_b32_e32 v4, 1, v0
	v_and_or_b32 v3, v2, 24, v3
	v_and_b32_e32 v4, 32, v4
	v_and_b32_e32 v2, 0x100, v2
	s_cmp_lg_u32 0, -1
	v_or3_b32 v2, v3, v4, v2
	s_cselect_b32 s0, 0, 0
	v_add_u32_e32 v221, s0, v2
	v_and_b32_e32 v2, 0x3fffffc0, v188
	v_add_u32_e32 v3, s75, v214
	v_ashrrev_i32_e32 v51, 31, v50
	v_lshl_add_u32 v2, v2, 2, s89
	s_waitcnt vmcnt(4)
	s_waitcnt vmcnt(7)
	ds_write_b128 v53, v[34:37] offset:16384
	s_waitcnt vmcnt(5)
	ds_write_b128 v54, v[38:41] offset:16384
	ds_write_b128 v3, v[42:45]
	v_add_u32_e32 v3, s75, v215
	s_waitcnt vmcnt(4)
	ds_write_b128 v3, v[46:49]
	v_cmp_gt_u32_e64 s[6:7], 32, v0
	v_lshl_add_u32 v212, v184, 2, v2
	v_lshl_add_u32 v210, v205, 2, v2
	v_sub_u32_e32 v0, v205, v184
	v_lshl_add_u64 v[2:3], v[50:51], 0, s[2:3]
	s_movk_i32 s2, 0x2400
	v_sub_u32_e32 v225, v0, v204
	v_mad_u64_u32 v[4:5], s[0:1], v2, s2, 0
	v_and_b32_e32 v0, 15, v188
	v_mad_i32_i24 v3, v3, s2, v5
	v_or_b32_e32 v2, s74, v4
	v_lshlrev_b32_e32 v0, 4, v0
	v_readlane_b32 s0, v254, 14
	v_lshl_add_u64 v[2:3], v[2:3], 0, v[0:1]
	v_readlane_b32 s1, v254, 15
	v_mov_b32_e32 v14, v1
	v_mov_b32_e32 v15, v1
	v_sub_u32_e32 v223, 0, v52
	v_lshl_add_u64 v[190:191], s[0:1], 0, v[2:3]
	v_mov_b32_e32 v0, v1
	v_mov_b32_e32 v2, v1
	v_mov_b32_e32 v3, v1
	v_mov_b32_e32 v4, v1
	v_mov_b32_e32 v5, v1
	v_mov_b32_e32 v6, v1
	v_mov_b32_e32 v7, v1
	v_mov_b32_e32 v8, v1
	v_mov_b32_e32 v9, v1
	v_mov_b32_e32 v10, v1
	v_mov_b32_e32 v11, v1
	v_mov_b32_e32 v12, v1
	v_mov_b32_e32 v13, v1
	v_mov_b64_e32 v[64:65], v[14:15]
	v_mov_b64_e32 v[48:49], v[14:15]
	v_mov_b64_e32 v[32:33], v[14:15]
	v_mov_b64_e32 v[62:63], v[12:13]
	v_mov_b64_e32 v[60:61], v[10:11]
	v_mov_b64_e32 v[58:59], v[8:9]
	v_mov_b64_e32 v[56:57], v[6:7]
	v_mov_b64_e32 v[54:55], v[4:5]
	v_mov_b64_e32 v[52:53], v[2:3]
	v_mov_b64_e32 v[50:51], v[0:1]
	v_mov_b64_e32 v[46:47], v[12:13]
	v_mov_b64_e32 v[44:45], v[10:11]
	v_mov_b64_e32 v[42:43], v[8:9]
	v_mov_b64_e32 v[40:41], v[6:7]
	v_mov_b64_e32 v[38:39], v[4:5]
	v_mov_b64_e32 v[36:37], v[2:3]
	v_mov_b64_e32 v[34:35], v[0:1]
	v_mov_b64_e32 v[30:31], v[12:13]
	v_mov_b64_e32 v[28:29], v[10:11]
	v_mov_b64_e32 v[26:27], v[8:9]
	v_mov_b64_e32 v[24:25], v[6:7]
	v_mov_b64_e32 v[22:23], v[4:5]
	v_mov_b64_e32 v[20:21], v[2:3]
	v_mov_b64_e32 v[18:19], v[0:1]
	v_mov_b64_e32 v[16:17], v[14:15]
	s_mov_b32 s66, 0
	s_mov_b32 s67, 2
	v_sub_u32_e32 v224, 0, v204
	v_mov_b32_e32 v213, 0
	s_movk_i32 s68, 0x4000
	s_mov_b32 s0, 0x8000
	v_mov_b64_e32 v[14:15], v[12:13]
	v_mov_b64_e32 v[12:13], v[10:11]
	v_mov_b64_e32 v[10:11], v[8:9]
	v_mov_b64_e32 v[8:9], v[6:7]
	v_mov_b64_e32 v[6:7], v[4:5]
	v_mov_b64_e32 v[4:5], v[2:3]
	v_mov_b64_e32 v[2:3], v[0:1]
	s_waitcnt vmcnt(0)
	v_readfirstlane_b32 s31, v179
	s_nop 3
	s_lshr_b32 s31, s31, 6
	s_lshl_b32 s30, s31, 11
	v_and_b32_e32 v150, 63, v179
	v_bfe_u32 v151, v150, 2, 3
	s_lshl_b32 s29, s31, 3
	v_or_b32_e32 v151, s29, v151
	v_and_b32_e32 v152, 4, v151
	v_lshlrev_b32_e32 v152, 1, v152
	v_and_b32_e32 v153, 8, v151
	v_lshrrev_b32_e32 v153, 1, v153
	v_and_b32_e32 v151, 0xfffffff3, v151
	v_or3_b32 v151, v151, v152, v153
	v_mul_u32_u24_e32 v151, 0x2400, v151
	v_lshrrev_b32_e32 v152, 5, v150
	v_lshlrev_b32_e32 v152, 6, v152
	v_and_b32_e32 v153, 3, v150
	v_lshlrev_b32_e32 v153, 4, v153
	v_add3_u32 v248, v151, v152, v153
	v_add_u32_e32 v249, 0x80, v248
	v_lshrrev_b32_e32 v151, 4, v150
	v_add_u32_e32 v151, s29, v151
	v_and_b32_e32 v152, 15, v150
	v_and_b32_e32 v153, 15, v151
	v_xor_b32_e32 v153, v152, v153
	v_mul_u32_u24_e32 v154, 0x2400, v151
	v_lshl_add_u32 v250, v153, 4, v154
	v_add_u32_e32 v151, 4, v151
	v_and_b32_e32 v153, 15, v151
	v_xor_b32_e32 v153, v152, v153
	v_mul_u32_u24_e32 v154, 0x2400, v151
	v_lshl_add_u32 v251, v153, 4, v154
	v_readfirstlane_b32 s26, v190
	v_readfirstlane_b32 s27, v191
	s_mul_i32 s29, s31, 0x9000
	s_add_u32 s29, s29, 0x168000
	s_sub_u32 s26, s26, s29
	s_subb_u32 s27, s27, 0
	s_sub_u32 s28, s26, 0x200
	s_subb_u32 s29, s27, 0
; __device__ __forceinline__ void finishSM(f32x16& p0, f32x16& p1, float alpha, float& l_reg, bf16x8& pa0, bf16x8& pa1, bf16x8& pa2, bf16x8& pa3) {
; #pragma unroll
;   for (int r = 0; r < 16; ++r) p1[r] = __builtin_amdgcn_exp2f(p1[r]);
;   float ps = 0;
; #pragma unroll
;   for (int r = 0; r < 16; ++r) ps += p0[r];
; #pragma unroll
;   for (int r = 0; r < 16; ++r) ps += p1[r];
;   { auto rr = __builtin_amdgcn_permlane32_swap(__float_as_uint(ps), __float_as_uint(ps), false, false);
;     ps = __uint_as_float(rr[0]) + __uint_as_float(rr[1]); }
;   l_reg = l_reg * alpha + ps;
;     ...
;   PK4(p0, 0, pa0); PK4(p0, 8, pa1); PK4(p1, 0, pa2); PK4(p1, 8, pa3);
;     ...
; }
; template <int ND0, int DOFF>
; __device__ __forceinline__ void qkt(f32x16& p0, f32x16& p1, const char* Ks, const bf16x8* qr, int r32, int hi) {
;   p0 = f32x16{}; p1 = f32x16{};
; #pragma unroll
;   for (int d0 = 0; d0 < ND0; ++d0) { const int cb = ((d0 + DOFF) * 16 + hi * 8) * 2;
;     bf16x8 b0 = *reinterpret_cast<const bf16x8*>(Ks + KSWZ(r32, cb));
;     bf16x8 b1 = *reinterpret_cast<const bf16x8*>(Ks + KSWZ(32 + r32, cb));
;     p0 = __builtin_amdgcn_mfma_f32_32x32x16_bf16(b0, qr[d0], p0, 0, 0, 0);
;     p1 = __builtin_amdgcn_mfma_f32_32x32x16_bf16(b1, qr[d0], p1, 0, 0, 0); }
; }
; __device__ __forceinline__ int v_st(int k, int c) { const int kk = (k & ~0xC) | ((k & 4) << 1) | ((k & 8) >> 1); return ((kk >> 3) * 4 + (c >> 5)) * 512 + ((kk & 7) * 32 + (c & 31)) * 2; }
; __device__ __forceinline__ int v_rd_base(int lane) { return ((lane & 3) << 3) | (((lane >> 2) & 3) << 6) | (((lane >> 4) & 1) << 5) | (((lane >> 5) & 1) << 8); }
; template <int OFF> __device__ __forceinline__ s16x4 tr_read(int vb) {
;   s16x4 r; asm volatile("ds_read_b64_tr_b16 %0, %1 offset:%2" : "=&v"(r) : "v"(vb), "i"(OFF) : "memory"); return r;
; }
; template <int MODE>
; __device__ __forceinline__ void attn_body(const bf16_t* __restrict__ Qb, const bf16_t* __restrict__ Kh, const bf16_t* __restrict__ Vh, int NT, int krel0,
;                                           char* lds, const float* __restrict__ lutg, const AttnEpi& E) {
;     ...
;   for (int j = 1; j + 1 < NT; j += 2) {
;     __syncthreads();
;     SBAR(); qkt<ND0, DOFF>(pB0, pB1, K_lds + oq, qr, r32, hi);
;     finishSM(pA0, pA1, alA, l_reg, pa0, pa1, pa2, pa3); SBAR();
;     SLOAD(SO, (j + 2) * 64); SBAR();
;     pv_d0(o, vb0 + op, pa0, pa1, pa2, pa3); PSM(pB0, pB1, mnB, alB, j);
.LBB0_177:
	v_readfirstlane_b32 s20, v224
	v_readfirstlane_b32 s21, v223
	s_nop 3
	s_add_i32 s22, s20, s77
	s_addk_i32 s22, 0x7f
	s_add_i32 s23, s21, s77
	s_addk_i32 s23, 0x40
	s_add_i32 s24, s22, 64
	s_add_i32 s25, s23, 64
	s_mov_b32 s2, s0
	s_waitcnt vmcnt(0) lgkmcnt(0)
	s_barrier
	s_add_i32 m0, s2, s30
	s_nop 0
	global_load_lds_dwordx4 v248, s[26:27]
	s_add_i32 m0, m0, 0x400
	s_nop 0
	global_load_lds_dwordx4 v249, s[26:27]
	s_add_i32 m0, m0, 0xbc00
	s_nop 0
	global_load_lds_dwordx4 v250, s[28:29]
	s_add_i32 m0, m0, 0x400
	s_nop 0
	global_load_lds_dwordx4 v251, s[28:29]
	s_add_u32 s26, s26, 0x90000
	s_addc_u32 s27, s27, 0
	s_add_u32 s28, s28, 0x90000
	s_addc_u32 s29, s29, 0
	s_add_i32 s0, s68, 0
	v_add_u32_e32 v0, s0, v216
	ds_read_b128 v[98:101], v0 offset:49152
	ds_read_b128 v[102:105], v0 offset:57344
	v_add_u32_e32 v0, s0, v217
	ds_read_b128 v[162:165], v0 offset:49152
	ds_read_b128 v[166:169], v0 offset:57344
	v_add_u32_e32 v0, s0, v218
	s_waitcnt lgkmcnt(3)
	v_mfma_f32_32x32x16_bf16 v[114:129], v[98:101], v[142:145], 0
	s_waitcnt lgkmcnt(2)
	v_mfma_f32_32x32x16_bf16 v[98:113], v[102:105], v[142:145], 0
	s_waitcnt lgkmcnt(1)
	v_mfma_f32_32x32x16_bf16 v[114:129], v[162:165], v[138:141], v[114:129]
	s_waitcnt lgkmcnt(0)
	v_mfma_f32_32x32x16_bf16 v[98:113], v[166:169], v[138:141], v[98:113]
	ds_read_b128 v[162:165], v0 offset:49152
	ds_read_b128 v[166:169], v0 offset:57344
	v_add_u32_e32 v0, s0, v219
	s_waitcnt lgkmcnt(1)
	v_mfma_f32_32x32x16_bf16 v[114:129], v[162:165], v[134:137], v[114:129]
	s_waitcnt lgkmcnt(0)
	v_mfma_f32_32x32x16_bf16 v[98:113], v[166:169], v[134:137], v[98:113]
	ds_read_b128 v[162:165], v0 offset:49152
	ds_read_b128 v[166:169], v0 offset:57344
	v_exp_f32_e32 v0, v82
	v_exp_f32_e32 v82, v83
	v_exp_f32_e32 v83, v84
	v_exp_f32_e32 v84, v85
	v_exp_f32_e32 v85, v86
	v_exp_f32_e32 v86, v87
	v_exp_f32_e32 v87, v88
	v_exp_f32_e32 v88, v89
	v_exp_f32_e32 v89, v90
	v_exp_f32_e32 v90, v91
	v_exp_f32_e32 v91, v92
	v_exp_f32_e32 v92, v93
	v_exp_f32_e32 v93, v94
	v_exp_f32_e32 v94, v95
	v_exp_f32_e32 v95, v96
	v_exp_f32_e32 v96, v97
	v_add_f32_e32 v97, v67, v66
	v_add_f32_e32 v97, v68, v97
	v_add_f32_e32 v97, v69, v97
	v_add_f32_e32 v97, v70, v97
	v_add_f32_e32 v97, v71, v97
	v_add_f32_e32 v97, v72, v97
	v_add_f32_e32 v97, v73, v97
	v_add_f32_e32 v97, v74, v97
	v_add_f32_e32 v97, v75, v97
	v_add_f32_e32 v97, v76, v97
	v_add_f32_e32 v97, v77, v97
	v_add_f32_e32 v97, v78, v97
	v_add_f32_e32 v97, v79, v97
	v_add_f32_e32 v97, v80, v97
	v_add_f32_e32 v97, v81, v97
	v_add_f32_e32 v97, v0, v97
	v_add_f32_e32 v97, v82, v97
	v_add_f32_e32 v97, v83, v97
	v_add_f32_e32 v97, v84, v97
	v_add_f32_e32 v97, v85, v97
	v_add_f32_e32 v97, v86, v97
	v_add_f32_e32 v97, v87, v97
	v_add_f32_e32 v97, v88, v97
	v_add_f32_e32 v97, v89, v97
	v_add_f32_e32 v97, v90, v97
	s_waitcnt lgkmcnt(1)
	v_mfma_f32_32x32x16_bf16 v[114:129], v[162:165], v[130:133], v[114:129]
	v_add_f32_e32 v97, v91, v97
	v_add_f32_e32 v97, v92, v97
	v_add_f32_e32 v97, v93, v97
	v_add_f32_e32 v97, v94, v97
	v_add_f32_e32 v97, v95, v97
	v_add_f32_e32 v226, v96, v97
	v_mov_b32_e32 v227, v226
	s_waitcnt lgkmcnt(0)
	v_mfma_f32_32x32x16_bf16 v[98:113], v[166:169], v[130:133], v[98:113]
	v_cvt_pk_bf16_f32 v66, v66, v67
	v_cvt_pk_bf16_f32 v67, v68, v69
	v_cvt_pk_bf16_f32 v68, v70, v71
	v_cvt_pk_bf16_f32 v69, v72, v73
	v_cvt_pk_bf16_f32 v70, v74, v75
	v_cvt_pk_bf16_f32 v71, v76, v77
	v_cvt_pk_bf16_f32 v72, v78, v79
	v_cvt_pk_bf16_f32 v73, v80, v81
	v_cvt_pk_bf16_f32 v74, v0, v82
	v_cvt_pk_bf16_f32 v75, v83, v84
	v_cvt_pk_bf16_f32 v76, v85, v86
	v_cvt_pk_bf16_f32 v77, v87, v88
	v_cvt_pk_bf16_f32 v78, v89, v90
	v_cvt_pk_bf16_f32 v79, v91, v92
	v_cvt_pk_bf16_f32 v80, v93, v94
	v_cvt_pk_bf16_f32 v81, v95, v96
	v_permlane32_swap_b32_e32 v226, v227
	v_permlane32_swap_b32_e32 v66, v68
	v_permlane32_swap_b32_e32 v67, v69
	v_permlane32_swap_b32_e32 v70, v72
	v_permlane32_swap_b32_e32 v71, v73
	v_permlane32_swap_b32_e32 v74, v76
	v_permlane32_swap_b32_e32 v75, v77
	v_permlane32_swap_b32_e32 v78, v80
	v_permlane32_swap_b32_e32 v79, v81
	v_add_u32_e32 v0, s66, v221
	ds_read_b64_tr_b16 v[82:83], v0 offset:0
	ds_read_b64_tr_b16 v[84:85], v0 offset:0x800
	ds_read_b64_tr_b16 v[86:87], v0 offset:0x1000
	ds_read_b64_tr_b16 v[88:89], v0 offset:0x1800
	ds_read_b64_tr_b16 v[90:91], v0 offset:0x2000
	ds_read_b64_tr_b16 v[92:93], v0 offset:0x2800
	ds_read_b64_tr_b16 v[94:95], v0 offset:0x3000
	ds_read_b64_tr_b16 v[96:97], v0 offset:0x3800
	s_waitcnt lgkmcnt(0)
	s_nop 0
	v_mfma_f32_32x32x16_bf16 v[50:65], v[66:69], v[82:85], v[50:65]
	ds_read_b64_tr_b16 v[82:83], v0 offset:0x200
	ds_read_b64_tr_b16 v[84:85], v0 offset:0xa00
	v_mfma_f32_32x32x16_bf16 v[50:65], v[70:73], v[86:89], v[50:65]
	ds_read_b64_tr_b16 v[86:87], v0 offset:0x1200
	ds_read_b64_tr_b16 v[88:89], v0 offset:0x1a00
	v_mfma_f32_32x32x16_bf16 v[50:65], v[74:77], v[90:93], v[50:65]
	ds_read_b64_tr_b16 v[90:91], v0 offset:0x2200
	ds_read_b64_tr_b16 v[92:93], v0 offset:0x2a00
	v_mfma_f32_32x32x16_bf16 v[50:65], v[78:81], v[94:97], v[50:65]
	ds_read_b64_tr_b16 v[94:95], v0 offset:0x3200
	ds_read_b64_tr_b16 v[96:97], v0 offset:0x3a00
	s_waitcnt lgkmcnt(0)
	v_mfma_f32_32x32x16_bf16 v[34:49], v[66:69], v[82:85], v[34:49]
	ds_read_b64_tr_b16 v[82:83], v0 offset:0x400
	ds_read_b64_tr_b16 v[84:85], v0 offset:0xc00
	v_mfma_f32_32x32x16_bf16 v[34:49], v[70:73], v[86:89], v[34:49]
	ds_read_b64_tr_b16 v[86:87], v0 offset:0x1400
	ds_read_b64_tr_b16 v[88:89], v0 offset:0x1c00
	v_mfma_f32_32x32x16_bf16 v[34:49], v[74:77], v[90:93], v[34:49]
	ds_read_b64_tr_b16 v[90:91], v0 offset:0x2400
	ds_read_b64_tr_b16 v[92:93], v0 offset:0x2c00
	v_mfma_f32_32x32x16_bf16 v[34:49], v[78:81], v[94:97], v[34:49]
	ds_read_b64_tr_b16 v[94:95], v0 offset:0x3400
	ds_read_b64_tr_b16 v[96:97], v0 offset:0x3c00
	s_waitcnt lgkmcnt(0)
	v_mfma_f32_32x32x16_bf16 v[18:33], v[66:69], v[82:85], v[18:33]
	ds_read_b64_tr_b16 v[82:83], v0 offset:0x600
	ds_read_b64_tr_b16 v[84:85], v0 offset:0xe00
	v_mfma_f32_32x32x16_bf16 v[18:33], v[70:73], v[86:89], v[18:33]
	ds_read_b64_tr_b16 v[86:87], v0 offset:0x1600
	ds_read_b64_tr_b16 v[88:89], v0 offset:0x1e00
	v_mfma_f32_32x32x16_bf16 v[18:33], v[74:77], v[90:93], v[18:33]
	ds_read_b64_tr_b16 v[90:91], v0 offset:0x2600
	ds_read_b64_tr_b16 v[92:93], v0 offset:0x2e00
	v_mfma_f32_32x32x16_bf16 v[18:33], v[78:81], v[94:97], v[18:33]
	ds_read_b64_tr_b16 v[94:95], v0 offset:0x3600
	ds_read_b64_tr_b16 v[96:97], v0 offset:0x3e00
	s_waitcnt lgkmcnt(0)
	v_mfma_f32_32x32x16_bf16 v[2:17], v[66:69], v[82:85], v[2:17]
	s_cmp_gt_i32 s95, s22
	s_cselect_b64 s[0:1], -1, 0
	s_cmp_lt_i32 s15, s22
	s_cselect_b64 vcc, -1, 0
	v_mov_b32_e32 v232, s76
	v_mfma_f32_32x32x16_bf16 v[2:17], v[70:73], v[86:89], v[2:17]
	v_mfma_f32_32x32x16_bf16 v[2:17], v[74:77], v[90:93], v[2:17]
	v_mfma_f32_32x32x16_bf16 v[2:17], v[78:81], v[94:97], v[2:17]
	s_and_saveexec_b64 s[58:59], vcc
	s_cbranch_execz .LBB0_181
; template <int MODE>
; __device__ __forceinline__ void partialSM(f32x16& p0, f32x16& p1, float& m_reg, float& mn, float& alpha, int relh, int relw_min, int relw_max, const float* lut) {
;     ...
;     if (nearT) {
; #pragma unroll
;       for (int r = 0; r < 16; ++r) { const int i0 = relh + (r & 3) + 8 * (r >> 2);
;         const int a0 = min(max(i0, -129), 129) + 129, a1 = min(max(i0 + 32, -129), 129) + 129;
;         p0[r] = fmaf(p0[r], C, lut[a0]); p1[r] = fmaf(p1[r], C, lut[a1]); }
	s_cmp_gt_i32 s91, s23
	s_cselect_b64 vcc, -1, 0
	s_mov_b64 s[62:63], -1
	s_and_saveexec_b64 s[60:61], vcc
	s_cbranch_execz .LBB0_180
	v_add_u32_e32 v230, s77, v225
	v_add_u32_e32 v66, 64, v230
	v_add_u32_e32 v68, 0x41, v230
	v_add_u32_e32 v70, 0x42, v230
	v_add_u32_e32 v72, 0x43, v230
	v_med3_i32 v67, v66, s39, v198
	v_med3_i32 v66, v66, s33, v199
	v_med3_i32 v69, v68, s39, v198
	v_med3_i32 v68, v68, s33, v199
	v_med3_i32 v71, v70, s39, v198
	v_med3_i32 v70, v70, s33, v199
	v_med3_i32 v73, v72, s39, v198
	v_med3_i32 v72, v72, s33, v199
	v_lshl_add_u32 v67, v67, 2, s76
	v_lshl_add_u32 v66, v66, 2, s76
	v_lshl_add_u32 v69, v69, 2, s76
	v_lshl_add_u32 v68, v68, 2, s76
	v_lshl_add_u32 v70, v70, 2, s76
	v_lshl_add_u32 v72, v72, 2, s76
	v_lshl_add_u32 v71, v71, 2, s76
	v_lshl_add_u32 v73, v73, 2, s76
	ds_read_b32 v194, v67 offset:516
	ds_read_b32 v66, v66 offset:644
	ds_read_b32 v195, v69 offset:516
	ds_read_b32 v67, v68 offset:644
	ds_read_b32 v232, v71 offset:516
	ds_read_b32 v68, v70 offset:644
	ds_read_b32 v233, v73 offset:516
	ds_read_b32 v69, v72 offset:644
	v_add_u32_e32 v70, 0x48, v230
	v_add_u32_e32 v72, 0x49, v230
	v_add_u32_e32 v74, 0x4a, v230
	v_add_u32_e32 v76, 0x4b, v230
	v_med3_i32 v71, v70, s39, v198
	v_med3_i32 v70, v70, s33, v199
	v_med3_i32 v73, v72, s39, v198
	v_med3_i32 v72, v72, s33, v199
	v_med3_i32 v75, v74, s39, v198
	v_med3_i32 v74, v74, s33, v199
	v_med3_i32 v77, v76, s39, v198
	v_med3_i32 v76, v76, s33, v199
	v_lshl_add_u32 v71, v71, 2, s76
	v_lshl_add_u32 v70, v70, 2, s76
	v_lshl_add_u32 v73, v73, 2, s76
	v_lshl_add_u32 v72, v72, 2, s76
	v_lshl_add_u32 v74, v74, 2, s76
	v_lshl_add_u32 v76, v76, 2, s76
	v_lshl_add_u32 v75, v75, 2, s76
	v_lshl_add_u32 v77, v77, 2, s76
	ds_read_b32 v234, v71 offset:516
	ds_read_b32 v70, v70 offset:644
	ds_read_b32 v235, v73 offset:516
	ds_read_b32 v71, v72 offset:644
	ds_read_b32 v236, v75 offset:516
	ds_read_b32 v72, v74 offset:644
	ds_read_b32 v237, v77 offset:516
	ds_read_b32 v73, v76 offset:644
	v_add_u32_e32 v74, 0x50, v230
	v_add_u32_e32 v76, 0x51, v230
	v_add_u32_e32 v78, 0x52, v230
	v_add_u32_e32 v80, 0x53, v230
	v_med3_i32 v75, v74, s39, v198
	v_med3_i32 v74, v74, s33, v199
	v_med3_i32 v77, v76, s39, v198
	v_med3_i32 v76, v76, s33, v199
	v_med3_i32 v79, v78, s39, v198
	v_med3_i32 v78, v78, s33, v199
	v_med3_i32 v81, v80, s39, v198
	v_med3_i32 v80, v80, s33, v199
	v_lshl_add_u32 v75, v75, 2, s76
	v_lshl_add_u32 v74, v74, 2, s76
	v_lshl_add_u32 v77, v77, 2, s76
	v_lshl_add_u32 v76, v76, 2, s76
	v_lshl_add_u32 v78, v78, 2, s76
	v_lshl_add_u32 v80, v80, 2, s76
	v_lshl_add_u32 v79, v79, 2, s76
	v_lshl_add_u32 v81, v81, 2, s76
	ds_read_b32 v238, v75 offset:516
	ds_read_b32 v74, v74 offset:644
	ds_read_b32 v239, v77 offset:516
	ds_read_b32 v75, v76 offset:644
	ds_read_b32 v240, v79 offset:516
	ds_read_b32 v76, v78 offset:644
	ds_read_b32 v241, v81 offset:516
	ds_read_b32 v77, v80 offset:644
	v_add_u32_e32 v78, 0x58, v230
	v_add_u32_e32 v80, 0x59, v230
	v_add_u32_e32 v82, 0x5a, v230
	v_med3_i32 v79, v78, s39, v198
	v_med3_i32 v78, v78, s33, v199
	v_med3_i32 v81, v80, s39, v198
	v_med3_i32 v80, v80, s33, v199
	v_med3_i32 v83, v82, s39, v198
	v_med3_i32 v82, v82, s33, v199
	v_add_u32_e32 v84, 0x5b, v230
	s_waitcnt lgkmcnt(14)
	v_fmac_f32_e32 v194, 0x3e38aa3b, v114
	v_fmac_f32_e32 v195, 0x3e38aa3b, v115
	v_lshl_add_u32 v79, v79, 2, s76
	v_lshl_add_u32 v78, v78, 2, s76
	v_lshl_add_u32 v81, v81, 2, s76
	v_lshl_add_u32 v80, v80, 2, s76
	v_lshl_add_u32 v82, v82, 2, s76
	v_med3_i32 v85, v84, s39, v198
	v_med3_i32 v84, v84, s33, v199
	v_fmac_f32_e32 v232, 0x3e38aa3b, v116
	v_fmac_f32_e32 v233, 0x3e38aa3b, v117
	v_lshl_add_u32 v83, v83, 2, s76
	v_lshl_add_u32 v85, v85, 2, s76
	v_lshl_add_u32 v84, v84, 2, s76
	ds_read_b32 v242, v79 offset:516
	ds_read_b32 v78, v78 offset:644
	ds_read_b32 v243, v81 offset:516
	ds_read_b32 v79, v80 offset:644
	ds_read_b32 v244, v83 offset:516
	ds_read_b32 v80, v82 offset:644
	ds_read_b32 v245, v85 offset:516
	ds_read_b32 v81, v84 offset:644
	v_max_f32_e32 v82, v194, v195
	v_fmac_f32_e32 v234, 0x3e38aa3b, v118
	s_waitcnt lgkmcnt(14)
; template <int MODE>
; __device__ __forceinline__ void partialSM(f32x16& p0, f32x16& p1, float& m_reg, float& mn, float& alpha, int relh, int relw_min, int relw_max, const float* lut) {
;     ...
;     float pmax = p0[0];
; #pragma unroll
;     for (int r = 1; r < 16; ++r) pmax = fmaxf(pmax, p0[r]);
; #pragma unroll
;     for (int r = 0; r < 16; ++r) pmax = fmaxf(pmax, p1[r]);
;     { auto rr = __builtin_amdgcn_permlane32_swap(__float_as_uint(pmax), __float_as_uint(pmax), false, false);
;       pmax = fmaxf(__uint_as_float(rr[0]), __uint_as_float(rr[1])); }
;     if (__builtin_expect(__all(pmax - m_reg <= THR2), 1)) { mn = m_reg; alpha = 1.f; }
;     else { mn = fmaxf(m_reg, pmax); alpha = __builtin_amdgcn_exp2f(m_reg - mn); m_reg = mn; }
; #pragma unroll
;     for (int r = 0; r < 16; ++r) p0[r] = __builtin_amdgcn_exp2f(p0[r] - mn);
; #pragma unroll
;     for (int r = 0; r < 16; ++r) p1[r] = p1[r] - mn;
	v_fmac_f32_e32 v235, 0x3e38aa3b, v119
	v_max3_f32 v82, v82, v232, v233
	v_fmac_f32_e32 v236, 0x3e38aa3b, v120
	v_fmac_f32_e32 v237, 0x3e38aa3b, v121
	v_max3_f32 v82, v82, v234, v235
	v_fmac_f32_e32 v238, 0x3e38aa3b, v122
	s_waitcnt lgkmcnt(13)
	v_fmac_f32_e32 v239, 0x3e38aa3b, v123
	v_max3_f32 v82, v82, v236, v237
	s_waitcnt lgkmcnt(11)
	v_fmac_f32_e32 v240, 0x3e38aa3b, v124
	s_waitcnt lgkmcnt(9)
	v_fmac_f32_e32 v241, 0x3e38aa3b, v125
	v_max3_f32 v82, v82, v238, v239
	s_waitcnt lgkmcnt(7)
	v_fmac_f32_e32 v242, 0x3e38aa3b, v126
	s_waitcnt lgkmcnt(5)
	v_fmac_f32_e32 v243, 0x3e38aa3b, v127
	v_max3_f32 v82, v82, v240, v241
	s_waitcnt lgkmcnt(3)
	v_fmac_f32_e32 v244, 0x3e38aa3b, v128
	s_waitcnt lgkmcnt(1)
	v_fmac_f32_e32 v245, 0x3e38aa3b, v129
	v_max3_f32 v82, v82, v242, v243
	v_max3_f32 v84, v82, v244, v245
	v_pk_fma_f32 v[82:83], v[98:99], s[48:49], v[66:67] op_sel_hi:[1,0,1]
	v_pk_fma_f32 v[86:87], v[102:103], s[48:49], v[70:71] op_sel_hi:[1,0,1]
	v_max3_f32 v66, v84, v82, v83
	v_pk_fma_f32 v[84:85], v[100:101], s[48:49], v[68:69] op_sel_hi:[1,0,1]
	v_pk_fma_f32 v[88:89], v[104:105], s[48:49], v[72:73] op_sel_hi:[1,0,1]
	v_max3_f32 v66, v66, v84, v85
	v_max3_f32 v66, v66, v86, v87
	v_max3_f32 v66, v66, v88, v89
	v_pk_fma_f32 v[90:91], v[106:107], s[48:49], v[74:75] op_sel_hi:[1,0,1]
	v_pk_fma_f32 v[92:93], v[108:109], s[48:49], v[76:77] op_sel_hi:[1,0,1]
	v_max3_f32 v66, v66, v90, v91
	v_max3_f32 v66, v66, v92, v93
	v_pk_fma_f32 v[94:95], v[110:111], s[48:49], v[78:79] op_sel_hi:[1,0,1]
	s_waitcnt lgkmcnt(0)
	v_pk_fma_f32 v[96:97], v[112:113], s[48:49], v[80:81] op_sel_hi:[1,0,1]
	v_max3_f32 v66, v66, v94, v95
	v_max3_f32 v66, v66, v96, v97
	v_mov_b32_e32 v67, v66
	s_nop 1
	v_permlane32_swap_b32_e32 v66, v67
	v_max_f32_e32 v66, v66, v67
	v_sub_f32_e32 v67, v66, v222
	v_cmp_ge_f32_e32 vcc, s94, v67
	v_max_f32_e32 v66, v222, v66
	v_sub_f32_e32 v67, v222, v66
	v_exp_f32_e32 v67, v67
	s_cmp_eq_u64 vcc, exec
	s_cselect_b64 vcc, -1, 0
	v_cndmask_b32_e32 v231, v66, v222, vcc
	v_cndmask_b32_e64 v229, v67, 1.0, vcc
	v_sub_f32_e32 v66, v194, v231
	v_sub_f32_e32 v67, v195, v231
	v_sub_f32_e32 v68, v232, v231
	v_sub_f32_e32 v69, v233, v231
	v_sub_f32_e32 v70, v234, v231
	v_sub_f32_e32 v71, v235, v231
	v_sub_f32_e32 v72, v236, v231
	v_sub_f32_e32 v73, v237, v231
	v_sub_f32_e32 v74, v238, v231
	v_sub_f32_e32 v75, v239, v231
	v_sub_f32_e32 v76, v240, v231
	v_sub_f32_e32 v77, v241, v231
	v_sub_f32_e32 v78, v242, v231
	v_sub_f32_e32 v79, v243, v231
	v_sub_f32_e32 v80, v244, v231
	v_sub_f32_e32 v81, v245, v231
	v_exp_f32_e32 v66, v66
	v_exp_f32_e32 v67, v67
	v_exp_f32_e32 v68, v68
	v_exp_f32_e32 v69, v69
	v_exp_f32_e32 v70, v70
	v_exp_f32_e32 v71, v71
	v_exp_f32_e32 v72, v72
	v_exp_f32_e32 v73, v73
	v_exp_f32_e32 v74, v74
	v_exp_f32_e32 v75, v75
	v_exp_f32_e32 v76, v76
	v_exp_f32_e32 v77, v77
	v_exp_f32_e32 v78, v78
	v_exp_f32_e32 v79, v79
	v_exp_f32_e32 v80, v80
	v_exp_f32_e32 v81, v81
	v_sub_f32_e32 v97, v97, v231
	v_sub_f32_e32 v96, v96, v231
	v_sub_f32_e32 v95, v95, v231
	v_sub_f32_e32 v94, v94, v231
	v_sub_f32_e32 v93, v93, v231
	v_sub_f32_e32 v92, v92, v231
	v_sub_f32_e32 v91, v91, v231
	v_sub_f32_e32 v90, v90, v231
	v_sub_f32_e32 v89, v89, v231
	v_sub_f32_e32 v88, v88, v231
	v_sub_f32_e32 v87, v87, v231
	v_sub_f32_e32 v86, v86, v231
	v_sub_f32_e32 v85, v85, v231
	v_sub_f32_e32 v84, v84, v231
	v_sub_f32_e32 v83, v83, v231
	v_sub_f32_e32 v82, v82, v231
	s_xor_b64 s[62:63], exec, -1

; #define SBAR() __builtin_amdgcn_sched_barrier(0)
; #define SLOAD(i, k0) do { sr_[i].vs0 = *reinterpret_cast<const bf16x8*>(&Vh[(size_t)((k0) + sr) * LDQK + sc]); sr_[i].vs1 = *reinterpret_cast<const bf16x8*>(&Vh[(size_t)((k0) + 32 + sr) * LDQK + sc]); \
;     sr_[i].ks0 = *reinterpret_cast<const bf16x8*>(&Kh[(size_t)((k0) + sr) * LDQK + sc]); sr_[i].ks1 = *reinterpret_cast<const bf16x8*>(&Kh[(size_t)((k0) + 32 + sr) * LDQK + sc]); } while (0)
; #define SWAIT() asm volatile("s_waitcnt vmcnt(4)" ::: "memory")
; __device__ __forceinline__ void finishSM(f32x16& p0, f32x16& p1, float alpha, float& l_reg, bf16x8& pa0, bf16x8& pa1, bf16x8& pa2, bf16x8& pa3) {
; #pragma unroll
;   for (int r = 0; r < 16; ++r) p1[r] = __builtin_amdgcn_exp2f(p1[r]);
;   float ps = 0;
; #pragma unroll
;   for (int r = 0; r < 16; ++r) ps += p0[r];
; #pragma unroll
;   for (int r = 0; r < 16; ++r) ps += p1[r];
;   { auto rr = __builtin_amdgcn_permlane32_swap(__float_as_uint(ps), __float_as_uint(ps), false, false);
;     ps = __uint_as_float(rr[0]) + __uint_as_float(rr[1]); }
;   l_reg = l_reg * alpha + ps;
;     ...
;   PK4(p0, 0, pa0); PK4(p0, 8, pa1); PK4(p1, 0, pa2); PK4(p1, 8, pa3);
;     ...
; }
; template <int ND0, int DOFF>
; __device__ __forceinline__ void qkt(f32x16& p0, f32x16& p1, const char* Ks, const bf16x8* qr, int r32, int hi) {
;   p0 = f32x16{}; p1 = f32x16{};
; #pragma unroll
;   for (int d0 = 0; d0 < ND0; ++d0) { const int cb = ((d0 + DOFF) * 16 + hi * 8) * 2;
;     bf16x8 b0 = *reinterpret_cast<const bf16x8*>(Ks + KSWZ(r32, cb));
;     bf16x8 b1 = *reinterpret_cast<const bf16x8*>(Ks + KSWZ(32 + r32, cb));
;     p0 = __builtin_amdgcn_mfma_f32_32x32x16_bf16(b0, qr[d0], p0, 0, 0, 0);
;     p1 = __builtin_amdgcn_mfma_f32_32x32x16_bf16(b1, qr[d0], p1, 0, 0, 0); }
; }
; template <int MODE>
; __device__ __forceinline__ void attn_body(const bf16_t* __restrict__ Qb, const bf16_t* __restrict__ Kh, const bf16_t* __restrict__ Vh, int NT, int krel0,
;                                           char* lds, const float* __restrict__ lutg, const AttnEpi& E) {
;     ...
;     SWAIT(); SWRITE(ow, SE);
;     RESC(alB);
;     { const int t = op; op = oq; oq = ow; ow = t; }
;     __syncthreads();
;     SBAR(); qkt<ND0, DOFF>(pA0, pA1, K_lds + oq, qr, r32, hi);
;     finishSM(pB0, pB1, alB, l_reg, pa0, pa1, pa2, pa3); SBAR();
;     if (j + 3 < NT) SLOAD(SE, (j + 3) * 64); SBAR();
.LBB0_183:
	s_or_b64 exec, exec, s[58:59]
	s_add_i32 s58, s2, 0
	v_cmp_gt_f32_e32 vcc, 1.0, v229
	s_cbranch_vccz .LBB0_187
	s_and_saveexec_b64 s[0:1], s[6:7]
	ds_write_b32 v212, v229 offset:128
	s_or_b64 exec, exec, s[0:1]
	s_waitcnt lgkmcnt(0)
	ds_read_b128 v[98:101], v210 offset:224
	ds_read_b128 v[102:105], v210 offset:192
	ds_read_b128 v[106:109], v210 offset:160
	ds_read_b128 v[110:113], v210 offset:128
	s_waitcnt lgkmcnt(3)
	v_pk_mul_f32 v[64:65], v[64:65], v[100:101]
	s_waitcnt lgkmcnt(2)
	v_pk_mul_f32 v[60:61], v[60:61], v[104:105]
	s_waitcnt lgkmcnt(1)
	v_pk_mul_f32 v[56:57], v[56:57], v[108:109]
	s_waitcnt lgkmcnt(0)
	v_pk_mul_f32 v[52:53], v[52:53], v[112:113]
	v_pk_mul_f32 v[62:63], v[62:63], v[98:99]
	v_pk_mul_f32 v[58:59], v[58:59], v[102:103]
	v_pk_mul_f32 v[54:55], v[54:55], v[106:107]
	v_pk_mul_f32 v[50:51], v[50:51], v[110:111]
	v_pk_mul_f32 v[48:49], v[48:49], v[100:101]
	v_pk_mul_f32 v[44:45], v[44:45], v[104:105]
	v_pk_mul_f32 v[40:41], v[40:41], v[108:109]
	v_pk_mul_f32 v[36:37], v[36:37], v[112:113]
	v_pk_mul_f32 v[46:47], v[46:47], v[98:99]
	v_pk_mul_f32 v[42:43], v[42:43], v[102:103]
	v_pk_mul_f32 v[38:39], v[38:39], v[106:107]
	v_pk_mul_f32 v[34:35], v[34:35], v[110:111]
	v_pk_mul_f32 v[32:33], v[32:33], v[100:101]
	v_pk_mul_f32 v[28:29], v[28:29], v[104:105]
	v_pk_mul_f32 v[24:25], v[24:25], v[108:109]
	v_pk_mul_f32 v[20:21], v[20:21], v[112:113]
	v_pk_mul_f32 v[30:31], v[30:31], v[98:99]
	v_pk_mul_f32 v[26:27], v[26:27], v[102:103]
	v_pk_mul_f32 v[22:23], v[22:23], v[106:107]
	v_pk_mul_f32 v[18:19], v[18:19], v[110:111]
	v_pk_mul_f32 v[16:17], v[16:17], v[100:101]
	v_pk_mul_f32 v[12:13], v[12:13], v[104:105]
	v_pk_mul_f32 v[8:9], v[8:9], v[108:109]
	v_pk_mul_f32 v[4:5], v[4:5], v[112:113]
	v_pk_mul_f32 v[14:15], v[14:15], v[98:99]
	v_pk_mul_f32 v[10:11], v[10:11], v[102:103]
	v_pk_mul_f32 v[6:7], v[6:7], v[106:107]
	v_pk_mul_f32 v[2:3], v[2:3], v[110:111]
.LBB0_187:
	s_waitcnt vmcnt(0) lgkmcnt(0)
	s_barrier
	s_add_i32 m0, s66, s30
	s_nop 0
	global_load_lds_dwordx4 v248, s[26:27]
	s_add_i32 m0, m0, 0x400
	s_nop 0
	global_load_lds_dwordx4 v249, s[26:27]
	s_add_i32 m0, m0, 0xbc00
	s_nop 0
	global_load_lds_dwordx4 v250, s[28:29]
	s_add_i32 m0, m0, 0x400
	s_nop 0
	global_load_lds_dwordx4 v251, s[28:29]
	s_add_u32 s26, s26, 0x90000
	s_addc_u32 s27, s27, 0
	s_add_u32 s28, s28, 0x90000
	s_addc_u32 s29, s29, 0
	v_add_u32_e32 v102, s58, v216
	ds_read_b128 v[98:101], v102 offset:49152
	ds_read_b128 v[102:105], v102 offset:57344
	v_add_u32_e32 v194, s58, v217
	ds_read_b128 v[232:235], v194 offset:49152
	ds_read_b128 v[236:239], v194 offset:57344
	v_add_u32_e32 v194, s58, v218
	s_waitcnt lgkmcnt(3)
	v_mfma_f32_32x32x16_bf16 v[114:129], v[98:101], v[142:145], 0
	v_exp_f32_e32 v82, v82
	v_exp_f32_e32 v83, v83
	v_exp_f32_e32 v84, v84
	v_exp_f32_e32 v85, v85
	v_exp_f32_e32 v86, v86
	v_exp_f32_e32 v87, v87
	v_exp_f32_e32 v88, v88
	s_waitcnt lgkmcnt(2)
	v_mfma_f32_32x32x16_bf16 v[98:113], v[102:105], v[142:145], 0
	v_exp_f32_e32 v89, v89
	v_exp_f32_e32 v90, v90
	v_exp_f32_e32 v91, v91
	v_exp_f32_e32 v92, v92
	v_exp_f32_e32 v93, v93
	v_exp_f32_e32 v94, v94
	v_exp_f32_e32 v95, v95
	s_waitcnt lgkmcnt(1)
	v_mfma_f32_32x32x16_bf16 v[114:129], v[232:235], v[138:141], v[114:129]
	v_exp_f32_e32 v96, v96
	v_exp_f32_e32 v97, v97
	s_waitcnt lgkmcnt(0)
	v_mfma_f32_32x32x16_bf16 v[98:113], v[236:239], v[138:141], v[98:113]
	ds_read_b128 v[232:235], v194 offset:49152
	ds_read_b128 v[236:239], v194 offset:57344
	v_add_u32_e32 v194, s58, v219
	s_waitcnt lgkmcnt(1)
	v_mfma_f32_32x32x16_bf16 v[114:129], v[232:235], v[134:137], v[114:129]
	s_waitcnt lgkmcnt(0)
	v_mfma_f32_32x32x16_bf16 v[98:113], v[236:239], v[134:137], v[98:113]
	ds_read_b128 v[232:235], v194 offset:49152
	ds_read_b128 v[236:239], v194 offset:57344
	v_add_f32_e32 v194, v67, v66
	v_add_f32_e32 v194, v68, v194
	v_add_f32_e32 v194, v69, v194
	v_add_f32_e32 v194, v70, v194
	v_add_f32_e32 v194, v71, v194
	v_add_f32_e32 v194, v72, v194
	v_add_f32_e32 v194, v73, v194
	v_add_f32_e32 v194, v74, v194
	v_add_f32_e32 v194, v75, v194
	v_add_f32_e32 v194, v76, v194
	v_add_f32_e32 v194, v77, v194
	v_add_f32_e32 v194, v78, v194
	v_add_f32_e32 v194, v79, v194
	v_add_f32_e32 v194, v80, v194
	v_add_f32_e32 v194, v81, v194
	v_add_f32_e32 v194, v82, v194
	v_add_f32_e32 v194, v83, v194
	v_add_f32_e32 v194, v84, v194
	v_add_f32_e32 v194, v85, v194
	v_add_f32_e32 v194, v86, v194
	v_add_f32_e32 v194, v87, v194
	v_add_f32_e32 v194, v88, v194
	v_add_f32_e32 v194, v89, v194
	v_add_f32_e32 v194, v90, v194
	v_add_f32_e32 v194, v91, v194
	s_waitcnt lgkmcnt(1)
	v_mfma_f32_32x32x16_bf16 v[114:129], v[232:235], v[130:133], v[114:129]
	v_add_f32_e32 v194, v92, v194
	v_add_f32_e32 v194, v93, v194
	v_add_f32_e32 v194, v94, v194
	v_add_f32_e32 v194, v95, v194
	v_add_f32_e32 v194, v96, v194
	v_add_f32_e32 v232, v97, v194
	v_mov_b32_e32 v233, v232
	s_waitcnt lgkmcnt(0)
	v_mfma_f32_32x32x16_bf16 v[98:113], v[236:239], v[130:133], v[98:113]
	v_cvt_pk_bf16_f32 v66, v66, v67
	v_cvt_pk_bf16_f32 v67, v68, v69
	v_cvt_pk_bf16_f32 v68, v70, v71
	v_cvt_pk_bf16_f32 v69, v72, v73
	v_cvt_pk_bf16_f32 v70, v74, v75
	v_cvt_pk_bf16_f32 v71, v76, v77
	v_cvt_pk_bf16_f32 v72, v78, v79
	v_cvt_pk_bf16_f32 v73, v80, v81
	v_cvt_pk_bf16_f32 v74, v82, v83
	v_cvt_pk_bf16_f32 v75, v84, v85
	v_cvt_pk_bf16_f32 v76, v86, v87
	v_cvt_pk_bf16_f32 v77, v88, v89
	v_cvt_pk_bf16_f32 v78, v90, v91
	v_cvt_pk_bf16_f32 v79, v92, v93
	v_cvt_pk_bf16_f32 v80, v94, v95
	v_cvt_pk_bf16_f32 v81, v96, v97
	v_permlane32_swap_b32_e32 v232, v233
	v_permlane32_swap_b32_e32 v66, v68
	v_permlane32_swap_b32_e32 v67, v69
	v_permlane32_swap_b32_e32 v70, v72
	v_permlane32_swap_b32_e32 v71, v73
	v_permlane32_swap_b32_e32 v74, v76
	v_permlane32_swap_b32_e32 v75, v77
	v_permlane32_swap_b32_e32 v78, v80
	v_permlane32_swap_b32_e32 v79, v81
	s_add_i32 s67, s67, 2
	s_cmp_ge_u32 s67, s11
	s_cselect_b64 s[0:1], -1, 0

; #define SWRITE(off, i) do { *(bf16x8*)(V_lds + (off) + vst0) = sr_[i].vs0;          \
;     *(bf16x8*)(V_lds + (off) + vst1) = sr_[i].vs1; int kc = sc * 2;               \
;     *(bf16x8*)(K_lds + (off) + KSWZ(sr, kc)) = sr_[i].ks0;                       \
;     *(bf16x8*)(K_lds + (off) + KSWZ(32 + sr, kc)) = sr_[i].ks1; } while (0)
; #define SWAIT() asm volatile("s_waitcnt vmcnt(4)" ::: "memory")
; #define RESC(a) do { if (__any((a) < 1.f)) { if (hi == 0) al_l[r32] = (a); asm volatile("s_waitcnt lgkmcnt(0)" ::: "memory"); \
;     _Pragma("unroll") for (int d = 0; d < 4; ++d) _Pragma("unroll") for (int r = 0; r < 16; ++r) o[d][r] *= al_l[crow(r, hi)]; } } while (0)
; template <int MODE>
; __device__ __forceinline__ void attn_body(const bf16_t* __restrict__ Qb, const bf16_t* __restrict__ Kh, const bf16_t* __restrict__ Vh, int NT, int krel0,
;                                           char* lds, const float* __restrict__ lutg, const AttnEpi& E) {
;     ...
;     SWAIT(); SWRITE(ow, SO);
;     RESC(alA);
.LBB0_195:
	s_or_b64 exec, exec, s[60:61]
	s_add_i32 s60, s66, 0
	v_cmp_gt_f32_e32 vcc, 1.0, v228
	s_cbranch_vccz .LBB0_199
	s_and_saveexec_b64 s[58:59], s[6:7]
	ds_write_b32 v212, v228 offset:128
	s_or_b64 exec, exec, s[58:59]
	s_waitcnt lgkmcnt(0)
	ds_read_b128 v[98:101], v210 offset:224
	ds_read_b128 v[102:105], v210 offset:192
	ds_read_b128 v[106:109], v210 offset:160
	ds_read_b128 v[110:113], v210 offset:128
	s_waitcnt lgkmcnt(3)
	v_pk_mul_f32 v[64:65], v[64:65], v[100:101]
	s_waitcnt lgkmcnt(2)
	v_pk_mul_f32 v[60:61], v[60:61], v[104:105]
	s_waitcnt lgkmcnt(1)
	v_pk_mul_f32 v[56:57], v[56:57], v[108:109]
	s_waitcnt lgkmcnt(0)
	v_pk_mul_f32 v[52:53], v[52:53], v[112:113]
	v_pk_mul_f32 v[62:63], v[62:63], v[98:99]
	v_pk_mul_f32 v[58:59], v[58:59], v[102:103]
	v_pk_mul_f32 v[54:55], v[54:55], v[106:107]
	v_pk_mul_f32 v[50:51], v[50:51], v[110:111]
	v_pk_mul_f32 v[48:49], v[48:49], v[100:101]
	v_pk_mul_f32 v[44:45], v[44:45], v[104:105]
	v_pk_mul_f32 v[40:41], v[40:41], v[108:109]
	v_pk_mul_f32 v[36:37], v[36:37], v[112:113]
	v_pk_mul_f32 v[46:47], v[46:47], v[98:99]
	v_pk_mul_f32 v[42:43], v[42:43], v[102:103]
	v_pk_mul_f32 v[38:39], v[38:39], v[106:107]
	v_pk_mul_f32 v[34:35], v[34:35], v[110:111]
	v_pk_mul_f32 v[32:33], v[32:33], v[100:101]
	v_pk_mul_f32 v[28:29], v[28:29], v[104:105]
	v_pk_mul_f32 v[24:25], v[24:25], v[108:109]
	v_pk_mul_f32 v[20:21], v[20:21], v[112:113]
	v_pk_mul_f32 v[30:31], v[30:31], v[98:99]
	v_pk_mul_f32 v[26:27], v[26:27], v[102:103]
	v_pk_mul_f32 v[22:23], v[22:23], v[106:107]
	v_pk_mul_f32 v[18:19], v[18:19], v[110:111]
	v_pk_mul_f32 v[16:17], v[16:17], v[100:101]
	v_pk_mul_f32 v[12:13], v[12:13], v[104:105]
	v_pk_mul_f32 v[8:9], v[8:9], v[108:109]
	v_pk_mul_f32 v[4:5], v[4:5], v[112:113]
	v_pk_mul_f32 v[14:15], v[14:15], v[98:99]
	v_pk_mul_f32 v[10:11], v[10:11], v[102:103]
	v_pk_mul_f32 v[6:7], v[6:7], v[106:107]
	v_pk_mul_f32 v[2:3], v[2:3], v[110:111]

; #define SBAR() __builtin_amdgcn_sched_barrier(0)
; __device__ __forceinline__ void finishSM(f32x16& p0, f32x16& p1, float alpha, float& l_reg, bf16x8& pa0, bf16x8& pa1, bf16x8& pa2, bf16x8& pa3) {
; #pragma unroll
;   for (int r = 0; r < 16; ++r) p1[r] = __builtin_amdgcn_exp2f(p1[r]);
;   float ps = 0;
; #pragma unroll
;   for (int r = 0; r < 16; ++r) ps += p0[r];
; #pragma unroll
;   for (int r = 0; r < 16; ++r) ps += p1[r];
;   { auto rr = __builtin_amdgcn_permlane32_swap(__float_as_uint(ps), __float_as_uint(ps), false, false);
;     ps = __uint_as_float(rr[0]) + __uint_as_float(rr[1]); }
;   l_reg = l_reg * alpha + ps;
;     ...
;   PK4(p0, 0, pa0); PK4(p0, 8, pa1); PK4(p1, 0, pa2); PK4(p1, 8, pa3);
;     ...
; }
; template <int ND0, int DOFF>
; __device__ __forceinline__ void qkt(f32x16& p0, f32x16& p1, const char* Ks, const bf16x8* qr, int r32, int hi) {
;   p0 = f32x16{}; p1 = f32x16{};
; #pragma unroll
;   for (int d0 = 0; d0 < ND0; ++d0) { const int cb = ((d0 + DOFF) * 16 + hi * 8) * 2;
;     bf16x8 b0 = *reinterpret_cast<const bf16x8*>(Ks + KSWZ(r32, cb));
;     bf16x8 b1 = *reinterpret_cast<const bf16x8*>(Ks + KSWZ(32 + r32, cb));
;     p0 = __builtin_amdgcn_mfma_f32_32x32x16_bf16(b0, qr[d0], p0, 0, 0, 0);
;     p1 = __builtin_amdgcn_mfma_f32_32x32x16_bf16(b1, qr[d0], p1, 0, 0, 0); }
; }
; __device__ __forceinline__ int v_st(int k, int c) { const int kk = (k & ~0xC) | ((k & 4) << 1) | ((k & 8) >> 1); return ((kk >> 3) * 4 + (c >> 5)) * 512 + ((kk & 7) * 32 + (c & 31)) * 2; }
; __device__ __forceinline__ int v_rd_base(int lane) { return ((lane & 3) << 3) | (((lane >> 2) & 3) << 6) | (((lane >> 4) & 1) << 5) | (((lane >> 5) & 1) << 8); }
; template <int OFF> __device__ __forceinline__ s16x4 tr_read(int vb) {
;   s16x4 r; asm volatile("ds_read_b64_tr_b16 %0, %1 offset:%2" : "=&v"(r) : "v"(vb), "i"(OFF) : "memory"); return r;
; }
; template <int MODE>
; __device__ __forceinline__ void attn_body(const bf16_t* __restrict__ Qb, const bf16_t* __restrict__ Kh, const bf16_t* __restrict__ Vh, int NT, int krel0,
;                                           char* lds, const float* __restrict__ lutg, const AttnEpi& E) {
;     ...
;   __syncthreads();
;   SBAR(); qkt<ND0, DOFF>(pB0, pB1, K_lds + oq, qr, r32, hi);
;   finishSM(pA0, pA1, alA, l_reg, pa0, pa1, pa2, pa3); SBAR();
;   pv_d0(o, vb0 + op, pa0, pa1, pa2, pa3); PSM(pB0, pB1, mnB, alB, NT - 1);
.LBB0_201:
	s_waitcnt vmcnt(0) lgkmcnt(0)
	s_barrier
	v_add_u32_e32 v102, s60, v216
	ds_read_b128 v[98:101], v102 offset:49152
	ds_read_b128 v[102:105], v102 offset:57344
	v_add_u32_e32 v146, s60, v217
	v_exp_f32_e32 v82, v82
	v_exp_f32_e32 v83, v83
	s_waitcnt lgkmcnt(1)
	v_mfma_f32_32x32x16_bf16 v[114:129], v[98:101], v[142:145], 0
	v_exp_f32_e32 v84, v84
	v_exp_f32_e32 v85, v85
	v_exp_f32_e32 v86, v86
	v_exp_f32_e32 v87, v87
	v_exp_f32_e32 v88, v88
	v_exp_f32_e32 v89, v89
	v_exp_f32_e32 v90, v90
	s_waitcnt lgkmcnt(0)
	v_mfma_f32_32x32x16_bf16 v[98:113], v[102:105], v[142:145], 0
	ds_read_b128 v[142:145], v146 offset:49152
	ds_read_b128 v[146:149], v146 offset:57344
	v_exp_f32_e32 v91, v91
	v_exp_f32_e32 v92, v92
	v_exp_f32_e32 v93, v93
	v_exp_f32_e32 v94, v94
	v_exp_f32_e32 v95, v95
	v_exp_f32_e32 v96, v96
	s_waitcnt lgkmcnt(1)
	v_mfma_f32_32x32x16_bf16 v[114:129], v[142:145], v[138:141], v[114:129]
	v_add_u32_e32 v142, s60, v218
	v_exp_f32_e32 v97, v97
	s_waitcnt lgkmcnt(0)
	v_mfma_f32_32x32x16_bf16 v[98:113], v[146:149], v[138:141], v[98:113]
	ds_read_b128 v[138:141], v142 offset:49152
	ds_read_b128 v[142:145], v142 offset:57344
	s_waitcnt lgkmcnt(1)
	v_mfma_f32_32x32x16_bf16 v[114:129], v[138:141], v[134:137], v[114:129]
	v_add_u32_e32 v138, s60, v219
	s_waitcnt lgkmcnt(0)
	v_mfma_f32_32x32x16_bf16 v[98:113], v[142:145], v[134:137], v[98:113]
	ds_read_b128 v[134:137], v138 offset:49152
	ds_read_b128 v[138:141], v138 offset:57344
	s_waitcnt lgkmcnt(1)
	v_mfma_f32_32x32x16_bf16 v[114:129], v[134:137], v[130:133], v[114:129]
	s_waitcnt lgkmcnt(0)
	v_mfma_f32_32x32x16_bf16 v[98:113], v[138:141], v[130:133], v[98:113]
	v_add_f32_e32 v130, 0, v66
	v_add_f32_e32 v130, v67, v130
	v_add_f32_e32 v130, v68, v130
	v_add_f32_e32 v130, v69, v130
	v_add_f32_e32 v130, v70, v130
	v_add_f32_e32 v130, v71, v130
	v_add_f32_e32 v130, v72, v130
	v_add_f32_e32 v130, v73, v130
	v_add_f32_e32 v130, v74, v130
	v_add_f32_e32 v130, v75, v130
	v_add_f32_e32 v130, v76, v130
	v_add_f32_e32 v130, v77, v130
	v_add_f32_e32 v130, v78, v130
	v_add_f32_e32 v130, v79, v130
	v_add_f32_e32 v130, v80, v130
	v_add_f32_e32 v130, v81, v130
	v_add_f32_e32 v130, v82, v130
	v_add_f32_e32 v130, v83, v130
	v_add_f32_e32 v130, v84, v130
	v_add_f32_e32 v130, v85, v130
	v_add_f32_e32 v130, v86, v130
	v_add_f32_e32 v130, v87, v130
	v_add_f32_e32 v130, v88, v130
	v_add_f32_e32 v130, v89, v130
	v_add_f32_e32 v130, v90, v130
	v_add_f32_e32 v130, v91, v130
	v_add_f32_e32 v130, v92, v130
	v_add_f32_e32 v130, v93, v130
	v_add_f32_e32 v130, v94, v130
	v_add_f32_e32 v130, v95, v130
	v_add_f32_e32 v130, v96, v130
	v_add_f32_e32 v130, v97, v130
	v_mov_b32_e32 v131, v130
	v_cvt_pk_bf16_f32 v66, v66, v67
	v_cvt_pk_bf16_f32 v67, v68, v69
	v_cvt_pk_bf16_f32 v68, v70, v71
	v_cvt_pk_bf16_f32 v69, v72, v73
	v_cvt_pk_bf16_f32 v70, v74, v75
	v_cvt_pk_bf16_f32 v71, v76, v77
	v_cvt_pk_bf16_f32 v72, v78, v79
	v_cvt_pk_bf16_f32 v73, v80, v81
	v_cvt_pk_bf16_f32 v74, v82, v83
	v_cvt_pk_bf16_f32 v75, v84, v85
	v_cvt_pk_bf16_f32 v76, v86, v87
	v_cvt_pk_bf16_f32 v77, v88, v89
	v_cvt_pk_bf16_f32 v78, v90, v91
	v_cvt_pk_bf16_f32 v79, v92, v93
	v_cvt_pk_bf16_f32 v80, v94, v95
	v_cvt_pk_bf16_f32 v81, v96, v97
	v_permlane32_swap_b32_e32 v130, v131
	v_permlane32_swap_b32_e32 v66, v68
	v_permlane32_swap_b32_e32 v67, v69
	v_permlane32_swap_b32_e32 v70, v72
	v_permlane32_swap_b32_e32 v71, v73
	v_permlane32_swap_b32_e32 v74, v76
	v_permlane32_swap_b32_e32 v75, v77
	v_permlane32_swap_b32_e32 v78, v80
	v_permlane32_swap_b32_e32 v79, v81
	v_add_u32_e32 v132, s2, v221
	ds_read_b64_tr_b16 v[82:83], v132 offset:0
	ds_read_b64_tr_b16 v[84:85], v132 offset:0x800
	ds_read_b64_tr_b16 v[86:87], v132 offset:0x1000
	ds_read_b64_tr_b16 v[88:89], v132 offset:0x1800
	ds_read_b64_tr_b16 v[90:91], v132 offset:0x2000
	ds_read_b64_tr_b16 v[92:93], v132 offset:0x2800
	ds_read_b64_tr_b16 v[94:95], v132 offset:0x3000
	ds_read_b64_tr_b16 v[96:97], v132 offset:0x3800
	s_waitcnt lgkmcnt(0)
	s_nop 0
	v_mfma_f32_32x32x16_bf16 v[50:65], v[66:69], v[82:85], v[50:65]
	ds_read_b64_tr_b16 v[82:83], v132 offset:0x200
	ds_read_b64_tr_b16 v[84:85], v132 offset:0xa00
	v_mfma_f32_32x32x16_bf16 v[50:65], v[70:73], v[86:89], v[50:65]
	ds_read_b64_tr_b16 v[86:87], v132 offset:0x1200
	ds_read_b64_tr_b16 v[88:89], v132 offset:0x1a00
	v_mfma_f32_32x32x16_bf16 v[50:65], v[74:77], v[90:93], v[50:65]
	ds_read_b64_tr_b16 v[90:91], v132 offset:0x2200
	ds_read_b64_tr_b16 v[92:93], v132 offset:0x2a00
	v_mfma_f32_32x32x16_bf16 v[50:65], v[78:81], v[94:97], v[50:65]
	ds_read_b64_tr_b16 v[94:95], v132 offset:0x3200
	ds_read_b64_tr_b16 v[96:97], v132 offset:0x3a00
	s_waitcnt lgkmcnt(0)
	v_mfma_f32_32x32x16_bf16 v[34:49], v[66:69], v[82:85], v[34:49]
	ds_read_b64_tr_b16 v[82:83], v132 offset:0x400
	ds_read_b64_tr_b16 v[84:85], v132 offset:0xc00
	v_mfma_f32_32x32x16_bf16 v[34:49], v[70:73], v[86:89], v[34:49]
	ds_read_b64_tr_b16 v[86:87], v132 offset:0x1400
	ds_read_b64_tr_b16 v[88:89], v132 offset:0x1c00
	v_mfma_f32_32x32x16_bf16 v[34:49], v[74:77], v[90:93], v[34:49]
	ds_read_b64_tr_b16 v[90:91], v132 offset:0x2400
	ds_read_b64_tr_b16 v[92:93], v132 offset:0x2c00
	v_mfma_f32_32x32x16_bf16 v[34:49], v[78:81], v[94:97], v[34:49]
	ds_read_b64_tr_b16 v[94:95], v132 offset:0x3400
	ds_read_b64_tr_b16 v[96:97], v132 offset:0x3c00
	s_waitcnt lgkmcnt(0)
	v_mfma_f32_32x32x16_bf16 v[18:33], v[66:69], v[82:85], v[18:33]
	ds_read_b64_tr_b16 v[82:83], v132 offset:0x600
	ds_read_b64_tr_b16 v[84:85], v132 offset:0xe00
	v_mfma_f32_32x32x16_bf16 v[18:33], v[70:73], v[86:89], v[18:33]
	ds_read_b64_tr_b16 v[86:87], v132 offset:0x1600
	ds_read_b64_tr_b16 v[88:89], v132 offset:0x1e00
	v_mfma_f32_32x32x16_bf16 v[18:33], v[74:77], v[90:93], v[18:33]
	ds_read_b64_tr_b16 v[90:91], v132 offset:0x2600
	ds_read_b64_tr_b16 v[92:93], v132 offset:0x2e00
	v_mfma_f32_32x32x16_bf16 v[18:33], v[78:81], v[94:97], v[18:33]
	ds_read_b64_tr_b16 v[94:95], v132 offset:0x3600
	ds_read_b64_tr_b16 v[96:97], v132 offset:0x3e00
	s_waitcnt lgkmcnt(0)
	v_mfma_f32_32x32x16_bf16 v[2:17], v[66:69], v[82:85], v[2:17]
	v_add_u32_e32 v66, s72, v208
	v_cmp_gt_i32_e64 s[0:1], s95, v66
	v_cmp_lt_i32_e32 vcc, s15, v66
	v_mov_b32_e32 v133, s76
	v_mfma_f32_32x32x16_bf16 v[2:17], v[70:73], v[86:89], v[2:17]
	v_mfma_f32_32x32x16_bf16 v[2:17], v[74:77], v[90:93], v[2:17]
	v_mfma_f32_32x32x16_bf16 v[2:17], v[78:81], v[94:97], v[2:17]
	s_and_saveexec_b64 s[58:59], vcc
	s_cbranch_execz .LBB0_206
; template <int MODE>
; __device__ __forceinline__ void partialSM(f32x16& p0, f32x16& p1, float& m_reg, float& mn, float& alpha, int relh, int relw_min, int relw_max, const float* lut) {
;     ...
;     if (nearT) {
; #pragma unroll
;       for (int r = 0; r < 16; ++r) { const int i0 = relh + (r & 3) + 8 * (r >> 2);
;         const int a0 = min(max(i0, -129), 129) + 129, a1 = min(max(i0 + 32, -129), 129) + 129;
;         p0[r] = fmaf(p0[r], C, lut[a0]); p1[r] = fmaf(p1[r], C, lut[a1]); }
	v_add_u32_e32 v66, s72, v207
	v_cmp_gt_i32_e32 vcc, s91, v66
	s_mov_b64 s[62:63], -1
	s_and_saveexec_b64 s[60:61], vcc
	s_cbranch_execz .LBB0_204
	v_add_u32_e32 v78, s72, v206
	v_add_u32_e32 v68, 1, v78
	v_add_u32_e32 v70, 2, v78
	v_add_u32_e32 v72, 3, v78
	v_med3_i32 v66, v78, s39, v198
	v_med3_i32 v67, v78, s33, v199
	v_med3_i32 v69, v68, s39, v198
	v_med3_i32 v68, v68, s33, v199
	v_med3_i32 v71, v70, s39, v198
	v_med3_i32 v70, v70, s33, v199
	v_med3_i32 v73, v72, s39, v198
	v_med3_i32 v72, v72, s33, v199
	v_lshl_add_u32 v66, v66, 2, s76
	v_lshl_add_u32 v67, v67, 2, s76
	v_lshl_add_u32 v69, v69, 2, s76
	v_lshl_add_u32 v68, v68, 2, s76
	v_lshl_add_u32 v70, v70, 2, s76
	v_lshl_add_u32 v72, v72, 2, s76
	v_lshl_add_u32 v71, v71, 2, s76
	v_lshl_add_u32 v73, v73, 2, s76
	ds_read_b32 v133, v66 offset:516
	ds_read_b32 v66, v67 offset:644
	ds_read_b32 v134, v69 offset:516
	ds_read_b32 v67, v68 offset:644
	ds_read_b32 v135, v71 offset:516
	ds_read_b32 v68, v70 offset:644
	ds_read_b32 v136, v73 offset:516
	ds_read_b32 v69, v72 offset:644
	v_add_u32_e32 v70, 8, v78
	v_add_u32_e32 v72, 9, v78
	v_add_u32_e32 v74, 10, v78
	v_add_u32_e32 v76, 11, v78
	v_med3_i32 v71, v70, s39, v198
	v_med3_i32 v70, v70, s33, v199
	v_med3_i32 v73, v72, s39, v198
	v_med3_i32 v72, v72, s33, v199
	v_med3_i32 v75, v74, s39, v198
	v_med3_i32 v74, v74, s33, v199
	v_med3_i32 v77, v76, s39, v198
	v_med3_i32 v76, v76, s33, v199
	v_lshl_add_u32 v71, v71, 2, s76
	v_lshl_add_u32 v70, v70, 2, s76
	v_lshl_add_u32 v73, v73, 2, s76
	v_lshl_add_u32 v72, v72, 2, s76
	v_lshl_add_u32 v74, v74, 2, s76
	v_lshl_add_u32 v76, v76, 2, s76
	v_lshl_add_u32 v75, v75, 2, s76
	v_lshl_add_u32 v77, v77, 2, s76
	ds_read_b32 v137, v71 offset:516
	ds_read_b32 v70, v70 offset:644
	ds_read_b32 v138, v73 offset:516
	ds_read_b32 v71, v72 offset:644
	ds_read_b32 v139, v75 offset:516
	ds_read_b32 v72, v74 offset:644
	ds_read_b32 v140, v77 offset:516
	ds_read_b32 v73, v76 offset:644
	v_add_u32_e32 v74, 16, v78
	v_add_u32_e32 v76, 17, v78
	v_add_u32_e32 v79, 18, v78
	v_add_u32_e32 v81, 19, v78
	v_med3_i32 v75, v74, s39, v198
	v_med3_i32 v74, v74, s33, v199
	v_med3_i32 v77, v76, s39, v198
	v_med3_i32 v76, v76, s33, v199
	v_med3_i32 v80, v79, s39, v198
	v_med3_i32 v79, v79, s33, v199
	v_med3_i32 v82, v81, s39, v198
	v_med3_i32 v81, v81, s33, v199
	v_lshl_add_u32 v75, v75, 2, s76
	v_lshl_add_u32 v74, v74, 2, s76
	v_lshl_add_u32 v77, v77, 2, s76
	v_lshl_add_u32 v76, v76, 2, s76
	v_lshl_add_u32 v79, v79, 2, s76
	v_lshl_add_u32 v81, v81, 2, s76
	v_lshl_add_u32 v80, v80, 2, s76
	v_lshl_add_u32 v82, v82, 2, s76
	ds_read_b32 v141, v75 offset:516
	ds_read_b32 v74, v74 offset:644
	ds_read_b32 v142, v77 offset:516
	ds_read_b32 v75, v76 offset:644
	ds_read_b32 v143, v80 offset:516
	ds_read_b32 v76, v79 offset:644
	ds_read_b32 v144, v82 offset:516
	ds_read_b32 v77, v81 offset:644
	v_add_u32_e32 v79, 24, v78
	v_add_u32_e32 v81, 25, v78
	v_med3_i32 v80, v79, s39, v198
	v_med3_i32 v79, v79, s33, v199
	v_med3_i32 v82, v81, s39, v198
	v_med3_i32 v81, v81, s33, v199
	v_add_u32_e32 v83, 26, v78
	v_add_u32_e32 v78, 27, v78
	s_waitcnt lgkmcnt(14)
	v_fmac_f32_e32 v133, 0x3e38aa3b, v114
	v_fmac_f32_e32 v134, 0x3e38aa3b, v115
	v_lshl_add_u32 v80, v80, 2, s76
	v_lshl_add_u32 v79, v79, 2, s76
	v_lshl_add_u32 v82, v82, 2, s76
	v_lshl_add_u32 v81, v81, 2, s76
	v_med3_i32 v84, v83, s39, v198
	v_med3_i32 v83, v83, s33, v199
	v_med3_i32 v85, v78, s39, v198
	v_med3_i32 v78, v78, s33, v199
	v_fmac_f32_e32 v135, 0x3e38aa3b, v116
	v_fmac_f32_e32 v136, 0x3e38aa3b, v117
	v_lshl_add_u32 v84, v84, 2, s76
	v_lshl_add_u32 v83, v83, 2, s76
	v_lshl_add_u32 v85, v85, 2, s76
	v_lshl_add_u32 v86, v78, 2, s76
	ds_read_b32 v145, v80 offset:516
	ds_read_b32 v78, v79 offset:644
	ds_read_b32 v146, v82 offset:516
	ds_read_b32 v79, v81 offset:644
	ds_read_b32 v147, v84 offset:516
	ds_read_b32 v80, v83 offset:644
	ds_read_b32 v148, v85 offset:516
	ds_read_b32 v81, v86 offset:644
	v_max_f32_e32 v82, v133, v134
	v_fmac_f32_e32 v137, 0x3e38aa3b, v118
	s_waitcnt lgkmcnt(14)
; template <int MODE>
; __device__ __forceinline__ void partialSM(f32x16& p0, f32x16& p1, float& m_reg, float& mn, float& alpha, int relh, int relw_min, int relw_max, const float* lut) {
;     ...
;     float pmax = p0[0];
; #pragma unroll
;     for (int r = 1; r < 16; ++r) pmax = fmaxf(pmax, p0[r]);
; #pragma unroll
;     for (int r = 0; r < 16; ++r) pmax = fmaxf(pmax, p1[r]);
;     { auto rr = __builtin_amdgcn_permlane32_swap(__float_as_uint(pmax), __float_as_uint(pmax), false, false);
;       pmax = fmaxf(__uint_as_float(rr[0]), __uint_as_float(rr[1])); }
;     if (__builtin_expect(__all(pmax - m_reg <= THR2), 1)) { mn = m_reg; alpha = 1.f; }
;     else { mn = fmaxf(m_reg, pmax); alpha = __builtin_amdgcn_exp2f(m_reg - mn); m_reg = mn; }
; #pragma unroll
;     for (int r = 0; r < 16; ++r) p0[r] = __builtin_amdgcn_exp2f(p0[r] - mn);
; #pragma unroll
;     for (int r = 0; r < 16; ++r) p1[r] = p1[r] - mn;
	v_fmac_f32_e32 v138, 0x3e38aa3b, v119
	v_max3_f32 v82, v82, v135, v136
	v_fmac_f32_e32 v139, 0x3e38aa3b, v120
	v_fmac_f32_e32 v140, 0x3e38aa3b, v121
	v_max3_f32 v82, v82, v137, v138
	v_fmac_f32_e32 v141, 0x3e38aa3b, v122
	s_waitcnt lgkmcnt(13)
	v_fmac_f32_e32 v142, 0x3e38aa3b, v123
	v_max3_f32 v82, v82, v139, v140
	s_waitcnt lgkmcnt(11)
	v_fmac_f32_e32 v143, 0x3e38aa3b, v124
	s_waitcnt lgkmcnt(9)
	v_fmac_f32_e32 v144, 0x3e38aa3b, v125
	v_max3_f32 v82, v82, v141, v142
	s_waitcnt lgkmcnt(7)
	v_fmac_f32_e32 v145, 0x3e38aa3b, v126
	s_waitcnt lgkmcnt(5)
	v_fmac_f32_e32 v146, 0x3e38aa3b, v127
	v_max3_f32 v82, v82, v143, v144
	s_waitcnt lgkmcnt(3)
	v_fmac_f32_e32 v147, 0x3e38aa3b, v128
	s_waitcnt lgkmcnt(1)
	v_fmac_f32_e32 v148, 0x3e38aa3b, v129
	v_max3_f32 v82, v82, v145, v146
	v_max3_f32 v84, v82, v147, v148
	v_pk_fma_f32 v[82:83], v[98:99], s[48:49], v[66:67] op_sel_hi:[1,0,1]
	v_pk_fma_f32 v[86:87], v[102:103], s[48:49], v[70:71] op_sel_hi:[1,0,1]
	v_max3_f32 v66, v84, v82, v83
	v_pk_fma_f32 v[84:85], v[100:101], s[48:49], v[68:69] op_sel_hi:[1,0,1]
	v_pk_fma_f32 v[88:89], v[104:105], s[48:49], v[72:73] op_sel_hi:[1,0,1]
	v_max3_f32 v66, v66, v84, v85
	v_max3_f32 v66, v66, v86, v87
	v_max3_f32 v66, v66, v88, v89
	v_pk_fma_f32 v[90:91], v[106:107], s[48:49], v[74:75] op_sel_hi:[1,0,1]
	v_pk_fma_f32 v[92:93], v[108:109], s[48:49], v[76:77] op_sel_hi:[1,0,1]
	v_max3_f32 v66, v66, v90, v91
	v_max3_f32 v66, v66, v92, v93
	v_pk_fma_f32 v[94:95], v[110:111], s[48:49], v[78:79] op_sel_hi:[1,0,1]
	s_waitcnt lgkmcnt(0)
	v_pk_fma_f32 v[96:97], v[112:113], s[48:49], v[80:81] op_sel_hi:[1,0,1]
	v_max3_f32 v66, v66, v94, v95
	v_max3_f32 v66, v66, v96, v97
	v_mov_b32_e32 v67, v66
	s_nop 1
	v_permlane32_swap_b32_e32 v66, v67
	v_max_f32_e32 v67, v67, v67
	v_max_f32_e32 v66, v66, v66
	v_max_f32_e32 v66, v66, v67
	v_sub_f32_e32 v67, v66, v222
	v_cmp_ge_f32_e32 vcc, s94, v67
	v_max_f32_e32 v67, v222, v222
	v_max_f32_e32 v66, v67, v66
	v_sub_f32_e32 v67, v222, v66
	v_exp_f32_e32 v67, v67
	s_cmp_eq_u64 vcc, exec
	s_cselect_b64 vcc, -1, 0
	v_cndmask_b32_e32 v149, v66, v222, vcc
	v_cndmask_b32_e64 v132, v67, 1.0, vcc
	v_sub_f32_e32 v66, v133, v149
	v_sub_f32_e32 v67, v134, v149
	v_sub_f32_e32 v68, v135, v149
	v_sub_f32_e32 v69, v136, v149
	v_sub_f32_e32 v70, v137, v149
	v_sub_f32_e32 v71, v138, v149
	v_sub_f32_e32 v72, v139, v149
	v_sub_f32_e32 v73, v140, v149
	v_sub_f32_e32 v74, v141, v149
	v_sub_f32_e32 v75, v142, v149
	v_sub_f32_e32 v76, v143, v149
	v_sub_f32_e32 v77, v144, v149
	v_sub_f32_e32 v78, v145, v149
	v_sub_f32_e32 v79, v146, v149
	v_sub_f32_e32 v80, v147, v149
	v_sub_f32_e32 v81, v148, v149
	v_exp_f32_e32 v66, v66
	v_exp_f32_e32 v67, v67
	v_exp_f32_e32 v68, v68
	v_exp_f32_e32 v69, v69
	v_exp_f32_e32 v70, v70
	v_exp_f32_e32 v71, v71
	v_exp_f32_e32 v72, v72
	v_exp_f32_e32 v73, v73
	v_exp_f32_e32 v74, v74
	v_exp_f32_e32 v75, v75
	v_exp_f32_e32 v76, v76
	v_exp_f32_e32 v77, v77
	v_exp_f32_e32 v78, v78
	v_exp_f32_e32 v79, v79
	v_exp_f32_e32 v80, v80
	v_exp_f32_e32 v81, v81
	v_sub_f32_e32 v97, v97, v149
	v_sub_f32_e32 v96, v96, v149
	v_sub_f32_e32 v95, v95, v149
	v_sub_f32_e32 v94, v94, v149
	v_sub_f32_e32 v93, v93, v149
	v_sub_f32_e32 v92, v92, v149
	v_sub_f32_e32 v91, v91, v149
	v_sub_f32_e32 v90, v90, v149
	v_sub_f32_e32 v89, v89, v149
	v_sub_f32_e32 v88, v88, v149
	v_sub_f32_e32 v87, v87, v149
	v_sub_f32_e32 v86, v86, v149
	v_sub_f32_e32 v85, v85, v149
	v_sub_f32_e32 v84, v84, v149
	v_sub_f32_e32 v83, v83, v149
	v_sub_f32_e32 v82, v82, v149
	s_xor_b64 s[62:63], exec, -1
